# S5-out: Toeplitz ring prologue loads issued at the unit header before table staging (staging registers moved)
# baseline (speedup 1.0000x reference)
; #define GAS __attribute__((address_space(1)))
; #define LAS __attribute__((address_space(3)))
; __device__ __forceinline__ v4u pack8(const float* x) { v4u w; w.x = pk2(x[0], x[1]); w.y = pk2(x[2], x[3]); w.z = pk2(x[4], x[5]); w.w = pk2(x[6], x[7]); return w; }
; __device__ __forceinline__ void ph_s5_out(Frame& F) {
;     ...
;     for (int u = F.vcu; u < 288; u += F.G) {
;         const int g = u / 9, nb = u % 9; int chunk = nb * 32 + r32; const bool valid = chunk < NCH; if (!valid) chunk = NCH - 1;
;         __syncthreads();
;         { const GAS v4u* tp = (const GAS v4u*)((const bf16*)(ws + WS_TOEP) + (size_t)g * 127 * 256); const float* t0 = (const float*)(ws + WS_T0) + (size_t)g * 512;
;           for (int c = tid; c < 127 * 32; c += 512) { const int di = c >> 5, p = (c >> 1) & 15, half = c & 1; v4u v;
;               if (di == 63) { float o[8];
; #pragma unroll
;                   for (int j = 0; j < 8; ++j) o[j] = t0[p * 16 + half * 8 + j] + t0[256 + p * 16 + half * 8 + j];
;                   v = pack8(o); }
;               else v = tp[c];
;               *(LAS v4u*)(L + (di * 16 + p) * TP_PITCH + half * 16) = v; } }
;         __syncthreads();
;         const bf16* ub = ug_frag_base(ws, g, nb, lane);
;         f32x16 acc[4];
; #pragma unroll
;         for (int i = 0; i < 4; ++i)
; #pragma unroll
;             for (int r = 0; r < 16; ++r) acc[i][r] = 0.f;
;         const LAS unsigned char* tl = L + ((63 + 2 * wave + (r32 >> 4)) * 16 + (r32 & 15)) * TP_PITCH + hh * 16;
; #pragma unroll 1
;         for (int s0 = 0; s0 < 64; s0 += 16) {
;             bf16x8_t bq[16];
; #pragma unroll
;             for (int e = 0; e < 16; ++e) bq[e] = *(const GAS bf16x8_t*)(ub + 512 * (s0 + e));
.LBB0_964:
	s_mul_hi_i32 s24, s48, 0x38e38e39
	s_lshr_b32 s25, s24, 31
	s_ashr_i32 s24, s24, 1
	s_add_i32 s26, s24, s25
	s_ashr_i32 s27, s26, 31
	s_mul_i32 s28, s26, 9
	s_sub_i32 s28, s48, s28
	s_lshl_b32 s29, s26, 3
	s_add_i32 s29, s29, s28
	s_cmp_lt_i32 s28, 8
	s_cselect_b32 s28, s29, s26
	s_cselect_b32 s34, s41, 0xdc00000
	s_ashr_i32 s29, s28, 31
	s_lshl_b64 s[28:29], s[28:29], 16
	s_add_u32 s28, s34, s28
	s_addc_u32 s29, 0, s29
	v_lshl_add_u64 v[82:83], v[76:77], 0, s[28:29]
	v_add_co_u32_e32 v82, vcc, 0xffffc000, v82
	s_nop 1
	v_addc_co_u32_e32 v83, vcc, -1, v83, vcc
	v_add_co_u32_e32 v210, vcc, 0x2000, v82
	s_nop 1
	v_addc_co_u32_e32 v211, vcc, 0, v83, vcc
	v_add_co_u32_e32 v212, vcc, 0x4000, v82
	s_nop 1
	v_addc_co_u32_e32 v213, vcc, 0, v83, vcc
	global_load_dwordx4 v[142:145], v[82:83], off offset:1024
	global_load_dwordx4 v[146:149], v[82:83], off offset:2048
	global_load_dwordx4 v[150:153], v[82:83], off offset:3072
	global_load_dwordx4 v[154:157], v[210:211], off offset:-4096
	global_load_dwordx4 v[158:161], v[210:211], off offset:-3072
	global_load_dwordx4 v[162:165], v[210:211], off offset:-2048
	global_load_dwordx4 v[166:169], v[210:211], off offset:-1024
	global_load_dwordx4 v[170:173], v[210:211], off offset:0
	global_load_dwordx4 v[174:177], v[210:211], off offset:1024
	global_load_dwordx4 v[178:181], v[210:211], off offset:2048
	global_load_dwordx4 v[182:185], v[210:211], off offset:3072
	global_load_dwordx4 v[190:193], v[212:213], off offset:-4096
	global_load_dwordx4 v[194:197], v[212:213], off offset:-3072
	global_load_dwordx4 v[198:201], v[212:213], off offset:-2048
	global_load_dwordx4 v[202:205], v[212:213], off offset:-1024
	global_load_dwordx4 v[206:209], v[212:213], off offset:0
	v_lshl_add_u64 v[82:83], v[82:83], 0, s[22:23]
	s_barrier
	s_and_saveexec_b64 s[24:25], s[2:3]
	s_cbranch_execz .LBB0_971
	s_lshl_b64 s[28:29], s[26:27], 11
	s_add_u32 s28, s36, s28
	v_mad_i64_i32 v[6:7], s[30:31], s26, v93, v[74:75]
	s_addc_u32 s29, s37, s29
	v_lshrrev_b32_e32 v216, 5, v236
	v_bfe_u32 v10, v236, 1, 4
	v_lshl_or_b32 v216, v216, 4, v10
	v_mad_u32_u24 v216, v216, 48, v72
	v_add_u32_e32 v217, 0xc000, v216
	global_load_dwordx4 v[96:99], v[6:7], off
	v_lshl_add_u64 v[214:215], v[6:7], 0, s[20:21]
	global_load_dwordx4 v[100:103], v[214:215], off
	v_lshl_add_u64 v[214:215], v[214:215], 0, s[20:21]
	global_load_dwordx4 v[104:107], v[214:215], off
	v_lshl_add_u64 v[214:215], v[214:215], 0, s[20:21]
	global_load_dwordx4 v[108:111], v[214:215], off
	v_lshl_add_u64 v[214:215], v[214:215], 0, s[20:21]
	global_load_dwordx4 v[112:115], v[214:215], off
	v_lshl_add_u64 v[214:215], v[214:215], 0, s[20:21]
	global_load_dwordx4 v[116:119], v[214:215], off
	v_lshl_add_u64 v[214:215], v[214:215], 0, s[20:21]
	global_load_dwordx4 v[120:123], v[214:215], off
	v_lshl_add_u64 v[214:215], v[214:215], 0, s[20:21]
	v_cmp_gt_u32_e32 vcc, 0x1e0, v236
	s_and_saveexec_b64 s[30:31], vcc
	global_load_dwordx4 v[124:127], v[214:215], off
	s_andn2_b64 exec, s[30:31], exec
	s_cbranch_execz .Ls5_t0_done
	v_lshl_or_b32 v11, v10, 6, v92
	global_load_dwordx4 v[128:131], v11, s[28:29] offset:1024
	global_load_dwordx4 v[132:135], v11, s[28:29]
	global_load_dwordx4 v[20:23], v11, s[28:29] offset:16
	global_load_dwordx4 v[24:27], v11, s[28:29] offset:1040
	s_waitcnt vmcnt(0)
	v_pk_add_f32 v[128:129], v[132:133], v[128:129]
	v_pk_add_f32 v[130:131], v[134:135], v[130:131]
	v_pk_add_f32 v[132:133], v[20:21], v[24:25]
	v_pk_add_f32 v[134:135], v[22:23], v[26:27]
	v_cvt_pk_bf16_f32 v108, v128, v129
	v_cvt_pk_bf16_f32 v109, v130, v131
	v_cvt_pk_bf16_f32 v110, v132, v133
	v_cvt_pk_bf16_f32 v111, v134, v135
.Ls5_t0_done:
	s_mov_b64 exec, s[30:31]
	s_waitcnt vmcnt(0)
	s_and_b64 exec, s[30:31], vcc
	ds_write_b128 v217, v[124:127] offset:36864
	s_mov_b64 exec, s[30:31]
	ds_write_b128 v216, v[96:99]
	ds_write_b128 v216, v[100:103] offset:12288
	ds_write_b128 v216, v[104:107] offset:24576
	ds_write_b128 v216, v[108:111] offset:36864
	ds_write_b128 v216, v[112:115] offset:49152
	ds_write_b128 v216, v[116:119] offset:61440
	ds_write_b128 v217, v[120:123] offset:24576
.LBB0_971:
	s_or_b64 exec, exec, s[24:25]
	s_mul_i32 s24, s26, 9
	s_sub_i32 s24, s48, s24
	s_lshl_b32 s30, s26, 3
	s_add_i32 s25, s30, s24
	s_cmp_lt_i32 s24, 8
	s_cselect_b32 s28, s25, s26
	s_cselect_b32 s25, s41, 0xdc00000
	s_ashr_i32 s29, s28, 31
	s_lshl_b64 s[28:29], s[28:29], 16
	s_add_u32 s28, s25, s28
	s_addc_u32 s29, 0, s29
	v_mov_b32_e32 v50, 0
	v_lshl_add_u64 v[82:83], v[76:77], 0, s[28:29]
	s_mov_b32 s25, -16
	v_mov_b32_e32 v68, v91
	v_mov_b32_e32 v51, v50
	v_mov_b32_e32 v52, v50
	v_mov_b32_e32 v53, v50
	v_mov_b32_e32 v54, v50
	v_mov_b32_e32 v55, v50
	v_mov_b32_e32 v56, v50
	v_mov_b32_e32 v57, v50
	v_mov_b32_e32 v58, v50
	v_mov_b32_e32 v59, v50
	v_mov_b32_e32 v60, v50
	v_mov_b32_e32 v61, v50
	v_mov_b32_e32 v62, v50
	v_mov_b32_e32 v63, v50
	v_mov_b32_e32 v64, v50
	v_mov_b32_e32 v65, v50
	v_mov_b32_e32 v34, v50
	v_mov_b32_e32 v35, v50
	v_mov_b32_e32 v36, v50
	v_mov_b32_e32 v37, v50
	v_mov_b32_e32 v38, v50
	v_mov_b32_e32 v39, v50
	v_mov_b32_e32 v40, v50
	v_mov_b32_e32 v41, v50
	v_mov_b32_e32 v42, v50
	v_mov_b32_e32 v43, v50
	v_mov_b32_e32 v44, v50
	v_mov_b32_e32 v45, v50
	v_mov_b32_e32 v46, v50
	v_mov_b32_e32 v47, v50
	v_mov_b32_e32 v48, v50
	v_mov_b32_e32 v49, v50
	v_mov_b32_e32 v18, v50
	v_mov_b32_e32 v19, v50
	v_mov_b32_e32 v20, v50
	v_mov_b32_e32 v21, v50
	v_mov_b32_e32 v22, v50
	v_mov_b32_e32 v23, v50
	v_mov_b32_e32 v24, v50
	v_mov_b32_e32 v25, v50
	v_mov_b32_e32 v26, v50
	v_mov_b32_e32 v27, v50
	v_mov_b32_e32 v28, v50
	v_mov_b32_e32 v29, v50
	v_mov_b32_e32 v30, v50
	v_mov_b32_e32 v31, v50
	v_mov_b32_e32 v32, v50
	v_mov_b32_e32 v33, v50
	v_mov_b32_e32 v2, v50
	v_mov_b32_e32 v3, v50
	v_mov_b32_e32 v4, v50
	v_mov_b32_e32 v5, v50
	v_mov_b32_e32 v6, v50
	v_mov_b32_e32 v7, v50
	v_mov_b32_e32 v8, v50
	v_mov_b32_e32 v9, v50
	v_mov_b32_e32 v10, v50
	v_mov_b32_e32 v11, v50
	v_mov_b32_e32 v12, v50
	v_mov_b32_e32 v13, v50
	v_mov_b32_e32 v14, v50
	v_mov_b32_e32 v15, v50
	v_mov_b32_e32 v16, v50
	v_mov_b32_e32 v17, v50
	s_waitcnt lgkmcnt(0)
	s_barrier
; #define GAS __attribute__((address_space(1)))
; #define LAS __attribute__((address_space(3)))
; __device__ __forceinline__ void ph_s5_out(Frame& F) {
;     ...
;         for (int s0 = 0; s0 < 64; s0 += 16) {
;             bf16x8_t bq[16];
; #pragma unroll
;             for (int e = 0; e < 16; ++e) bq[e] = *(const GAS bf16x8_t*)(ub + 512 * (s0 + e));
; #pragma unroll
;             for (int e = 0; e < 16; ++e) { const int sI = s0 + e; const bf16x8_t b = bq[e];
; #pragma unroll
;             for (int i = 0; i < 4; ++i) { const bf16x8_t a = *(const LAS bf16x8_t*)(tl + (16 * i - sI) * 16 * TP_PITCH); acc[i] = __builtin_amdgcn_mfma_f32_32x32x16_bf16(a, b, acc[i], 0, 0, 0); }
;             }
.LBB0_972:
	v_add_co_u32_e32 v210, vcc, 0x2000, v82
	s_nop 1
	v_addc_co_u32_e32 v211, vcc, 0, v83, vcc
	v_add_co_u32_e32 v212, vcc, 0x4000, v82
	s_nop 1
	v_addc_co_u32_e32 v213, vcc, 0, v83, vcc
	ds_read_b128 v[84:87], v68 offset:11520
	ds_read_b128 v[96:99], v68 offset:12288
	s_waitcnt vmcnt(15) lgkmcnt(1)
	v_mfma_f32_32x32x16_bf16 v[50:65], v[84:87], v[142:145], v[50:65]
	ds_read_b128 v[84:87], v68 offset:23808
	ds_read_b128 v[108:111], v68 offset:24576
	s_waitcnt lgkmcnt(1)
	v_mfma_f32_32x32x16_bf16 v[34:49], v[84:87], v[142:145], v[34:49]
	ds_read_b128 v[84:87], v68 offset:36096
	ds_read_b128 v[112:115], v68 offset:36864
	s_waitcnt lgkmcnt(1)
	v_mfma_f32_32x32x16_bf16 v[18:33], v[84:87], v[142:145], v[18:33]
	ds_read_b128 v[84:87], v68 offset:48384
	ds_read_b128 v[116:119], v68
	s_waitcnt lgkmcnt(1)
	v_mfma_f32_32x32x16_bf16 v[2:17], v[84:87], v[142:145], v[2:17]
	global_load_dwordx4 v[142:145], v[82:83], off offset:1024
	ds_read_b128 v[84:87], v68 offset:10752
	ds_read_b128 v[100:103], v68 offset:9984
	s_waitcnt vmcnt(15) lgkmcnt(1)
	v_mfma_f32_32x32x16_bf16 v[50:65], v[84:87], v[146:149], v[50:65]
	ds_read_b128 v[84:87], v68 offset:23040
	ds_read_b128 v[120:123], v68 offset:22272
	s_waitcnt lgkmcnt(1)
	v_mfma_f32_32x32x16_bf16 v[34:49], v[84:87], v[146:149], v[34:49]
	ds_read_b128 v[84:87], v68 offset:35328
	ds_read_b128 v[124:127], v68 offset:34560
	ds_read_b128 v[128:131], v68 offset:46848
	s_waitcnt lgkmcnt(2)
	v_mfma_f32_32x32x16_bf16 v[18:33], v[84:87], v[146:149], v[18:33]
	ds_read_b128 v[84:87], v68 offset:47616
	s_waitcnt lgkmcnt(0)
	v_mfma_f32_32x32x16_bf16 v[2:17], v[84:87], v[146:149], v[2:17]
	global_load_dwordx4 v[146:149], v[82:83], off offset:2048
	s_waitcnt vmcnt(15)
	v_mfma_f32_32x32x16_bf16 v[50:65], v[100:103], v[150:153], v[50:65]
	v_mfma_f32_32x32x16_bf16 v[34:49], v[120:123], v[150:153], v[34:49]
	ds_read_b128 v[100:103], v68 offset:9216
	ds_read_b128 v[120:123], v68 offset:8448
	v_mfma_f32_32x32x16_bf16 v[18:33], v[124:127], v[150:153], v[18:33]
	v_mfma_f32_32x32x16_bf16 v[2:17], v[128:131], v[150:153], v[2:17]
	global_load_dwordx4 v[150:153], v[82:83], off offset:3072
	s_waitcnt vmcnt(15) lgkmcnt(1)
	v_mfma_f32_32x32x16_bf16 v[50:65], v[100:103], v[154:157], v[50:65]
	ds_read_b128 v[100:103], v68 offset:21504
	ds_read_b128 v[128:131], v68 offset:20736
	s_waitcnt lgkmcnt(1)
	v_mfma_f32_32x32x16_bf16 v[34:49], v[100:103], v[154:157], v[34:49]
	ds_read_b128 v[100:103], v68 offset:33792
	ds_read_b128 v[132:135], v68 offset:33024
	s_waitcnt lgkmcnt(1)
	v_mfma_f32_32x32x16_bf16 v[18:33], v[100:103], v[154:157], v[18:33]
	ds_read_b128 v[100:103], v68 offset:46080
	ds_read_b128 v[136:139], v68 offset:45312
	s_waitcnt lgkmcnt(1)
	v_mfma_f32_32x32x16_bf16 v[2:17], v[100:103], v[154:157], v[2:17]
	global_load_dwordx4 v[154:157], v[210:211], off offset:-4096
	s_waitcnt vmcnt(15)
	v_mfma_f32_32x32x16_bf16 v[50:65], v[120:123], v[158:161], v[50:65]
	ds_read_b128 v[100:103], v68 offset:7680
	ds_read_b128 v[120:123], v68 offset:6912
	v_mfma_f32_32x32x16_bf16 v[34:49], v[128:131], v[158:161], v[34:49]
	v_mfma_f32_32x32x16_bf16 v[18:33], v[132:135], v[158:161], v[18:33]
	s_waitcnt lgkmcnt(2)
	v_mfma_f32_32x32x16_bf16 v[2:17], v[136:139], v[158:161], v[2:17]
	global_load_dwordx4 v[158:161], v[210:211], off offset:-3072
	s_waitcnt vmcnt(15) lgkmcnt(1)
	v_mfma_f32_32x32x16_bf16 v[50:65], v[100:103], v[162:165], v[50:65]
	ds_read_b128 v[100:103], v68 offset:19968
	ds_read_b128 v[128:131], v68 offset:19200
	s_waitcnt lgkmcnt(1)
	v_mfma_f32_32x32x16_bf16 v[34:49], v[100:103], v[162:165], v[34:49]
	ds_read_b128 v[100:103], v68 offset:32256
	ds_read_b128 v[132:135], v68 offset:31488
	s_waitcnt lgkmcnt(1)
	v_mfma_f32_32x32x16_bf16 v[18:33], v[100:103], v[162:165], v[18:33]
	ds_read_b128 v[100:103], v68 offset:44544
	ds_read_b128 v[136:139], v68 offset:43776
	s_waitcnt lgkmcnt(1)
	v_mfma_f32_32x32x16_bf16 v[2:17], v[100:103], v[162:165], v[2:17]
	global_load_dwordx4 v[162:165], v[210:211], off offset:-2048
	s_waitcnt vmcnt(15)
	v_mfma_f32_32x32x16_bf16 v[50:65], v[120:123], v[166:169], v[50:65]
	ds_read_b128 v[100:103], v68 offset:6144
	ds_read_b128 v[120:123], v68 offset:5376
	v_mfma_f32_32x32x16_bf16 v[34:49], v[128:131], v[166:169], v[34:49]
	v_mfma_f32_32x32x16_bf16 v[18:33], v[132:135], v[166:169], v[18:33]
	s_waitcnt lgkmcnt(2)
	v_mfma_f32_32x32x16_bf16 v[2:17], v[136:139], v[166:169], v[2:17]
	global_load_dwordx4 v[166:169], v[210:211], off offset:-1024
	s_waitcnt vmcnt(15) lgkmcnt(1)
	v_mfma_f32_32x32x16_bf16 v[50:65], v[100:103], v[170:173], v[50:65]
	ds_read_b128 v[100:103], v68 offset:18432
	ds_read_b128 v[124:127], v68 offset:17664
	s_waitcnt lgkmcnt(1)
	v_mfma_f32_32x32x16_bf16 v[34:49], v[100:103], v[170:173], v[34:49]
	ds_read_b128 v[100:103], v68 offset:30720
	ds_read_b128 v[128:131], v68 offset:29952
	s_waitcnt lgkmcnt(1)
	v_mfma_f32_32x32x16_bf16 v[18:33], v[100:103], v[170:173], v[18:33]
	ds_read_b128 v[100:103], v68 offset:43008
	ds_read_b128 v[132:135], v68 offset:42240
	s_waitcnt lgkmcnt(1)
	v_mfma_f32_32x32x16_bf16 v[2:17], v[100:103], v[170:173], v[2:17]
	global_load_dwordx4 v[170:173], v[210:211], off offset:0
	ds_read_b128 v[84:87], v68 offset:4608
	ds_read_b128 v[100:103], v68 offset:3840
	s_waitcnt vmcnt(15)
	v_mfma_f32_32x32x16_bf16 v[50:65], v[120:123], v[174:177], v[50:65]
	v_mfma_f32_32x32x16_bf16 v[34:49], v[124:127], v[174:177], v[34:49]
	v_mfma_f32_32x32x16_bf16 v[18:33], v[128:131], v[174:177], v[18:33]
	s_waitcnt lgkmcnt(2)
	v_mfma_f32_32x32x16_bf16 v[2:17], v[132:135], v[174:177], v[2:17]
	global_load_dwordx4 v[174:177], v[210:211], off offset:1024
	s_waitcnt vmcnt(15) lgkmcnt(1)
; #define GAS __attribute__((address_space(1)))
; #define LAS __attribute__((address_space(3)))
; __device__ __forceinline__ void ph_s5_out(Frame& F) {
;     ...
;         for (int s0 = 0; s0 < 64; s0 += 16) {
;             bf16x8_t bq[16];
; #pragma unroll
;             for (int e = 0; e < 16; ++e) bq[e] = *(const GAS bf16x8_t*)(ub + 512 * (s0 + e));
; #pragma unroll
;             for (int e = 0; e < 16; ++e) { const int sI = s0 + e; const bf16x8_t b = bq[e];
; #pragma unroll
;             for (int i = 0; i < 4; ++i) { const bf16x8_t a = *(const LAS bf16x8_t*)(tl + (16 * i - sI) * 16 * TP_PITCH); acc[i] = __builtin_amdgcn_mfma_f32_32x32x16_bf16(a, b, acc[i], 0, 0, 0); }
;             }
;         }
;         { const bf16* sb = (const bf16*)(ws + WS_SIN) + (size_t)g * 9 * 16 * 512 + ((size_t)nb * 16 * 64 + lane) * 8;
;           const bf16* wc = (const bf16*)(ws + WS_WC) + (size_t)g * 1024 * 256 + (((size_t)wave * 16) * 64 + lane) * 8;
; #pragma unroll 4
;           for (int kk = 0; kk < 16; ++kk) {
;               const bf16x8_t b = *(const GAS bf16x8_t*)(sb + 512 * kk);
; #pragma unroll
;               for (int i = 0; i < 4; ++i) { const bf16x8_t a = *(const GAS bf16x8_t*)(wc + (size_t)(8 * i) * 16 * 512 + 512 * kk); acc[i] = __builtin_amdgcn_mfma_f32_32x32x16_bf16(a, b, acc[i], 0, 0, 0); }
;           } }
	v_mfma_f32_32x32x16_bf16 v[50:65], v[84:87], v[178:181], v[50:65]
	ds_read_b128 v[84:87], v68 offset:16896
	ds_read_b128 v[124:127], v68 offset:16128
	s_waitcnt lgkmcnt(1)
	v_mfma_f32_32x32x16_bf16 v[34:49], v[84:87], v[178:181], v[34:49]
	ds_read_b128 v[84:87], v68 offset:29184
	ds_read_b128 v[128:131], v68 offset:28416
	s_waitcnt lgkmcnt(1)
	v_mfma_f32_32x32x16_bf16 v[18:33], v[84:87], v[178:181], v[18:33]
	ds_read_b128 v[84:87], v68 offset:41472
	ds_read_b128 v[132:135], v68 offset:40704
	s_waitcnt lgkmcnt(1)
	v_mfma_f32_32x32x16_bf16 v[2:17], v[84:87], v[178:181], v[2:17]
	global_load_dwordx4 v[178:181], v[210:211], off offset:2048
	s_waitcnt vmcnt(15)
	v_mfma_f32_32x32x16_bf16 v[50:65], v[100:103], v[182:185], v[50:65]
	v_mfma_f32_32x32x16_bf16 v[34:49], v[124:127], v[182:185], v[34:49]
	v_mfma_f32_32x32x16_bf16 v[18:33], v[128:131], v[182:185], v[18:33]
	s_waitcnt lgkmcnt(0)
	v_mfma_f32_32x32x16_bf16 v[2:17], v[132:135], v[182:185], v[2:17]
	global_load_dwordx4 v[182:185], v[210:211], off offset:3072
	ds_read_b128 v[104:107], v68 offset:3072
	ds_read_b128 v[120:123], v68 offset:2304
	s_waitcnt vmcnt(15) lgkmcnt(1)
	v_mfma_f32_32x32x16_bf16 v[50:65], v[104:107], v[190:193], v[50:65]
	ds_read_b128 v[104:107], v68 offset:15360
	ds_read_b128 v[124:127], v68 offset:14592
	s_waitcnt lgkmcnt(1)
	v_mfma_f32_32x32x16_bf16 v[34:49], v[104:107], v[190:193], v[34:49]
	ds_read_b128 v[104:107], v68 offset:27648
	ds_read_b128 v[128:131], v68 offset:26880
	s_waitcnt lgkmcnt(1)
	v_mfma_f32_32x32x16_bf16 v[18:33], v[104:107], v[190:193], v[18:33]
	ds_read_b128 v[104:107], v68 offset:39936
	ds_read_b128 v[132:135], v68 offset:39168
	s_waitcnt lgkmcnt(1)
	v_mfma_f32_32x32x16_bf16 v[2:17], v[104:107], v[190:193], v[2:17]
	global_load_dwordx4 v[190:193], v[212:213], off offset:-4096
	s_waitcnt vmcnt(15)
	v_mfma_f32_32x32x16_bf16 v[50:65], v[120:123], v[194:197], v[50:65]
	v_mfma_f32_32x32x16_bf16 v[34:49], v[124:127], v[194:197], v[34:49]
	v_mfma_f32_32x32x16_bf16 v[18:33], v[128:131], v[194:197], v[18:33]
	s_waitcnt lgkmcnt(0)
	v_mfma_f32_32x32x16_bf16 v[2:17], v[132:135], v[194:197], v[2:17]
	global_load_dwordx4 v[194:197], v[212:213], off offset:-3072
	ds_read_b128 v[100:103], v68 offset:1536
	ds_read_b128 v[120:123], v68 offset:768
	s_waitcnt vmcnt(15) lgkmcnt(1)
	v_mfma_f32_32x32x16_bf16 v[50:65], v[100:103], v[198:201], v[50:65]
	ds_read_b128 v[100:103], v68 offset:13824
	ds_read_b128 v[124:127], v68 offset:13056
	s_waitcnt lgkmcnt(1)
	v_mfma_f32_32x32x16_bf16 v[34:49], v[100:103], v[198:201], v[34:49]
	ds_read_b128 v[100:103], v68 offset:26112
	ds_read_b128 v[128:131], v68 offset:25344
	s_waitcnt lgkmcnt(1)
	v_mfma_f32_32x32x16_bf16 v[18:33], v[100:103], v[198:201], v[18:33]
	ds_read_b128 v[100:103], v68 offset:38400
	ds_read_b128 v[132:135], v68 offset:37632
	v_add_u32_e32 v68, 0xffffd000, v68
	s_waitcnt lgkmcnt(1)
	v_mfma_f32_32x32x16_bf16 v[2:17], v[100:103], v[198:201], v[2:17]
	global_load_dwordx4 v[198:201], v[212:213], off offset:-2048
	s_waitcnt vmcnt(15)
	v_mfma_f32_32x32x16_bf16 v[50:65], v[120:123], v[202:205], v[50:65]
	v_mfma_f32_32x32x16_bf16 v[34:49], v[124:127], v[202:205], v[34:49]
	v_mfma_f32_32x32x16_bf16 v[18:33], v[128:131], v[202:205], v[18:33]
	s_waitcnt lgkmcnt(0)
	v_mfma_f32_32x32x16_bf16 v[2:17], v[132:135], v[202:205], v[2:17]
	global_load_dwordx4 v[202:205], v[212:213], off offset:-1024
	s_waitcnt vmcnt(15)
	v_mfma_f32_32x32x16_bf16 v[50:65], v[116:119], v[206:209], v[50:65]
	v_mfma_f32_32x32x16_bf16 v[34:49], v[96:99], v[206:209], v[34:49]
	v_mfma_f32_32x32x16_bf16 v[18:33], v[108:111], v[206:209], v[18:33]
	v_mfma_f32_32x32x16_bf16 v[2:17], v[112:115], v[206:209], v[2:17]
	global_load_dwordx4 v[206:209], v[212:213], off offset:0
	v_lshl_add_u64 v[82:83], v[82:83], 0, s[22:23]
	s_add_i32 s25, s25, 16
	s_cmp_gt_u32 s25, 31
	s_cbranch_scc0 .LBB0_972
	s_ashr_i32 s25, s24, 31
	s_mul_i32 s49, s26, 0x24000
	s_lshl_b64 s[28:29], s[24:25], 14
	s_lshl_b64 s[34:35], s[26:27], 19
	s_mul_hi_i32 s31, s26, 0x24000
	s_add_u32 s28, s49, s28
	s_addc_u32 s29, s31, s29
	s_add_u32 s28, s28, 0x800
	s_addc_u32 s29, s29, 0
	s_add_u32 s34, s34, 0x9901000
	s_addc_u32 s35, s35, 0
	v_lshl_add_u64 v[88:89], v[80:81], 0, s[28:29]
	v_lshl_add_u64 v[214:215], v[78:79], 0, s[34:35]
	s_mov_b64 s[28:29], 0x20000
	v_lshl_add_u64 v[216:217], v[214:215], 0, s[28:29]
	v_lshl_add_u64 v[140:141], v[216:217], 0, s[28:29]
	v_lshl_add_u64 v[186:187], v[140:141], 0, s[28:29]
	ds_read_b128 v[84:87], v68 offset:11520
	ds_read_b128 v[96:99], v68 offset:12288
	s_waitcnt vmcnt(15) lgkmcnt(1)
	v_mfma_f32_32x32x16_bf16 v[50:65], v[84:87], v[142:145], v[50:65]
	ds_read_b128 v[84:87], v68 offset:23808
	ds_read_b128 v[108:111], v68 offset:24576
	s_waitcnt lgkmcnt(1)
	v_mfma_f32_32x32x16_bf16 v[34:49], v[84:87], v[142:145], v[34:49]
	ds_read_b128 v[84:87], v68 offset:36096
	ds_read_b128 v[112:115], v68 offset:36864
	s_waitcnt lgkmcnt(1)
	v_mfma_f32_32x32x16_bf16 v[18:33], v[84:87], v[142:145], v[18:33]
	ds_read_b128 v[84:87], v68 offset:48384
	ds_read_b128 v[116:119], v68
	s_waitcnt lgkmcnt(1)
	v_mfma_f32_32x32x16_bf16 v[2:17], v[84:87], v[142:145], v[2:17]
	global_load_dwordx4 v[142:145], v[88:89], off offset:-4096
	ds_read_b128 v[84:87], v68 offset:10752
	ds_read_b128 v[100:103], v68 offset:9984
	s_waitcnt vmcnt(15) lgkmcnt(1)
	v_mfma_f32_32x32x16_bf16 v[50:65], v[84:87], v[146:149], v[50:65]
	ds_read_b128 v[84:87], v68 offset:23040
	ds_read_b128 v[120:123], v68 offset:22272
	s_waitcnt lgkmcnt(1)
	v_mfma_f32_32x32x16_bf16 v[34:49], v[84:87], v[146:149], v[34:49]
	ds_read_b128 v[84:87], v68 offset:35328
	ds_read_b128 v[124:127], v68 offset:34560
	ds_read_b128 v[128:131], v68 offset:46848
	s_waitcnt lgkmcnt(2)
; #define GAS __attribute__((address_space(1)))
; #define LAS __attribute__((address_space(3)))
; __device__ __forceinline__ void ph_s5_out(Frame& F) {
;     ...
;             for (int e = 0; e < 16; ++e) { const int sI = s0 + e; const bf16x8_t b = bq[e];
; #pragma unroll
;             for (int i = 0; i < 4; ++i) { const bf16x8_t a = *(const LAS bf16x8_t*)(tl + (16 * i - sI) * 16 * TP_PITCH); acc[i] = __builtin_amdgcn_mfma_f32_32x32x16_bf16(a, b, acc[i], 0, 0, 0); }
;             }
;         }
;         { const bf16* sb = (const bf16*)(ws + WS_SIN) + (size_t)g * 9 * 16 * 512 + ((size_t)nb * 16 * 64 + lane) * 8;
;           const bf16* wc = (const bf16*)(ws + WS_WC) + (size_t)g * 1024 * 256 + (((size_t)wave * 16) * 64 + lane) * 8;
; #pragma unroll 4
;           for (int kk = 0; kk < 16; ++kk) {
;               const bf16x8_t b = *(const GAS bf16x8_t*)(sb + 512 * kk);
; #pragma unroll
;               for (int i = 0; i < 4; ++i) { const bf16x8_t a = *(const GAS bf16x8_t*)(wc + (size_t)(8 * i) * 16 * 512 + 512 * kk); acc[i] = __builtin_amdgcn_mfma_f32_32x32x16_bf16(a, b, acc[i], 0, 0, 0); }
	v_mfma_f32_32x32x16_bf16 v[18:33], v[84:87], v[146:149], v[18:33]
	ds_read_b128 v[84:87], v68 offset:47616
	s_waitcnt lgkmcnt(0)
	v_mfma_f32_32x32x16_bf16 v[2:17], v[84:87], v[146:149], v[2:17]
	global_load_dwordx4 v[146:149], v[214:215], off offset:-4096
	s_waitcnt vmcnt(15)
	v_mfma_f32_32x32x16_bf16 v[50:65], v[100:103], v[150:153], v[50:65]
	v_mfma_f32_32x32x16_bf16 v[34:49], v[120:123], v[150:153], v[34:49]
	ds_read_b128 v[100:103], v68 offset:9216
	ds_read_b128 v[120:123], v68 offset:8448
	v_mfma_f32_32x32x16_bf16 v[18:33], v[124:127], v[150:153], v[18:33]
	v_mfma_f32_32x32x16_bf16 v[2:17], v[128:131], v[150:153], v[2:17]
	global_load_dwordx4 v[150:153], v[216:217], off offset:-4096
	s_waitcnt vmcnt(15) lgkmcnt(1)
	v_mfma_f32_32x32x16_bf16 v[50:65], v[100:103], v[154:157], v[50:65]
	ds_read_b128 v[100:103], v68 offset:21504
	ds_read_b128 v[128:131], v68 offset:20736
	s_waitcnt lgkmcnt(1)
	v_mfma_f32_32x32x16_bf16 v[34:49], v[100:103], v[154:157], v[34:49]
	ds_read_b128 v[100:103], v68 offset:33792
	ds_read_b128 v[132:135], v68 offset:33024
	s_waitcnt lgkmcnt(1)
	v_mfma_f32_32x32x16_bf16 v[18:33], v[100:103], v[154:157], v[18:33]
	ds_read_b128 v[100:103], v68 offset:46080
	ds_read_b128 v[136:139], v68 offset:45312
	s_waitcnt lgkmcnt(1)
	v_mfma_f32_32x32x16_bf16 v[2:17], v[100:103], v[154:157], v[2:17]
	global_load_dwordx4 v[154:157], v[140:141], off offset:-4096
	s_waitcnt vmcnt(15)
	v_mfma_f32_32x32x16_bf16 v[50:65], v[120:123], v[158:161], v[50:65]
	ds_read_b128 v[100:103], v68 offset:7680
	ds_read_b128 v[120:123], v68 offset:6912
	v_mfma_f32_32x32x16_bf16 v[34:49], v[128:131], v[158:161], v[34:49]
	v_mfma_f32_32x32x16_bf16 v[18:33], v[132:135], v[158:161], v[18:33]
	s_waitcnt lgkmcnt(2)
	v_mfma_f32_32x32x16_bf16 v[2:17], v[136:139], v[158:161], v[2:17]
	global_load_dwordx4 v[158:161], v[186:187], off offset:-4096
	s_waitcnt vmcnt(15) lgkmcnt(1)
	v_mfma_f32_32x32x16_bf16 v[50:65], v[100:103], v[162:165], v[50:65]
	ds_read_b128 v[100:103], v68 offset:19968
	ds_read_b128 v[128:131], v68 offset:19200
	s_waitcnt lgkmcnt(1)
	v_mfma_f32_32x32x16_bf16 v[34:49], v[100:103], v[162:165], v[34:49]
	ds_read_b128 v[100:103], v68 offset:32256
	ds_read_b128 v[132:135], v68 offset:31488
	s_waitcnt lgkmcnt(1)
	v_mfma_f32_32x32x16_bf16 v[18:33], v[100:103], v[162:165], v[18:33]
	ds_read_b128 v[100:103], v68 offset:44544
	ds_read_b128 v[136:139], v68 offset:43776
	s_waitcnt lgkmcnt(1)
	v_mfma_f32_32x32x16_bf16 v[2:17], v[100:103], v[162:165], v[2:17]
	global_load_dwordx4 v[162:165], v[88:89], off offset:-3072
	s_waitcnt vmcnt(15)
	v_mfma_f32_32x32x16_bf16 v[50:65], v[120:123], v[166:169], v[50:65]
	ds_read_b128 v[100:103], v68 offset:6144
	ds_read_b128 v[120:123], v68 offset:5376
	v_mfma_f32_32x32x16_bf16 v[34:49], v[128:131], v[166:169], v[34:49]
	v_mfma_f32_32x32x16_bf16 v[18:33], v[132:135], v[166:169], v[18:33]
	s_waitcnt lgkmcnt(2)
	v_mfma_f32_32x32x16_bf16 v[2:17], v[136:139], v[166:169], v[2:17]
	global_load_dwordx4 v[166:169], v[214:215], off offset:-3072
	s_waitcnt vmcnt(15) lgkmcnt(1)
	v_mfma_f32_32x32x16_bf16 v[50:65], v[100:103], v[170:173], v[50:65]
	ds_read_b128 v[100:103], v68 offset:18432
	ds_read_b128 v[124:127], v68 offset:17664
	s_waitcnt lgkmcnt(1)
	v_mfma_f32_32x32x16_bf16 v[34:49], v[100:103], v[170:173], v[34:49]
	ds_read_b128 v[100:103], v68 offset:30720
	ds_read_b128 v[128:131], v68 offset:29952
	s_waitcnt lgkmcnt(1)
	v_mfma_f32_32x32x16_bf16 v[18:33], v[100:103], v[170:173], v[18:33]
	ds_read_b128 v[100:103], v68 offset:43008
	ds_read_b128 v[132:135], v68 offset:42240
	s_waitcnt lgkmcnt(1)
	v_mfma_f32_32x32x16_bf16 v[2:17], v[100:103], v[170:173], v[2:17]
	global_load_dwordx4 v[170:173], v[216:217], off offset:-3072
	ds_read_b128 v[84:87], v68 offset:4608
	ds_read_b128 v[100:103], v68 offset:3840
	s_waitcnt vmcnt(15)
	v_mfma_f32_32x32x16_bf16 v[50:65], v[120:123], v[174:177], v[50:65]
	v_mfma_f32_32x32x16_bf16 v[34:49], v[124:127], v[174:177], v[34:49]
	v_mfma_f32_32x32x16_bf16 v[18:33], v[128:131], v[174:177], v[18:33]
	s_waitcnt lgkmcnt(2)
	v_mfma_f32_32x32x16_bf16 v[2:17], v[132:135], v[174:177], v[2:17]
	global_load_dwordx4 v[174:177], v[140:141], off offset:-3072
	s_waitcnt vmcnt(15) lgkmcnt(1)
	v_mfma_f32_32x32x16_bf16 v[50:65], v[84:87], v[178:181], v[50:65]
	ds_read_b128 v[84:87], v68 offset:16896
	ds_read_b128 v[124:127], v68 offset:16128
	s_waitcnt lgkmcnt(1)
	v_mfma_f32_32x32x16_bf16 v[34:49], v[84:87], v[178:181], v[34:49]
	ds_read_b128 v[84:87], v68 offset:29184
	ds_read_b128 v[128:131], v68 offset:28416
	s_waitcnt lgkmcnt(1)
	v_mfma_f32_32x32x16_bf16 v[18:33], v[84:87], v[178:181], v[18:33]
	ds_read_b128 v[84:87], v68 offset:41472
	ds_read_b128 v[132:135], v68 offset:40704
	s_waitcnt lgkmcnt(1)
	v_mfma_f32_32x32x16_bf16 v[2:17], v[84:87], v[178:181], v[2:17]
	global_load_dwordx4 v[178:181], v[186:187], off offset:-3072
	s_waitcnt vmcnt(15)
	v_mfma_f32_32x32x16_bf16 v[50:65], v[100:103], v[182:185], v[50:65]
	v_mfma_f32_32x32x16_bf16 v[34:49], v[124:127], v[182:185], v[34:49]
	v_mfma_f32_32x32x16_bf16 v[18:33], v[128:131], v[182:185], v[18:33]
	s_waitcnt lgkmcnt(0)
	v_mfma_f32_32x32x16_bf16 v[2:17], v[132:135], v[182:185], v[2:17]
	global_load_dwordx4 v[182:185], v[88:89], off offset:-2048
	ds_read_b128 v[104:107], v68 offset:3072
	ds_read_b128 v[120:123], v68 offset:2304
	s_waitcnt vmcnt(15) lgkmcnt(1)
	v_mfma_f32_32x32x16_bf16 v[50:65], v[104:107], v[190:193], v[50:65]
	ds_read_b128 v[104:107], v68 offset:15360
	ds_read_b128 v[124:127], v68 offset:14592
	s_waitcnt lgkmcnt(1)
	v_mfma_f32_32x32x16_bf16 v[34:49], v[104:107], v[190:193], v[34:49]
	ds_read_b128 v[104:107], v68 offset:27648
	ds_read_b128 v[128:131], v68 offset:26880
	s_waitcnt lgkmcnt(1)
; #define GAS __attribute__((address_space(1)))
; __device__ __forceinline__ void ph_s5_out(Frame& F) {
;     ...
;         { const bf16* sb = (const bf16*)(ws + WS_SIN) + (size_t)g * 9 * 16 * 512 + ((size_t)nb * 16 * 64 + lane) * 8;
;           const bf16* wc = (const bf16*)(ws + WS_WC) + (size_t)g * 1024 * 256 + (((size_t)wave * 16) * 64 + lane) * 8;
; #pragma unroll 4
;           for (int kk = 0; kk < 16; ++kk) {
;               const bf16x8_t b = *(const GAS bf16x8_t*)(sb + 512 * kk);
; #pragma unroll
;               for (int i = 0; i < 4; ++i) { const bf16x8_t a = *(const GAS bf16x8_t*)(wc + (size_t)(8 * i) * 16 * 512 + 512 * kk); acc[i] = __builtin_amdgcn_mfma_f32_32x32x16_bf16(a, b, acc[i], 0, 0, 0); }
;           } }
	v_mfma_f32_32x32x16_bf16 v[18:33], v[104:107], v[190:193], v[18:33]
	ds_read_b128 v[104:107], v68 offset:39936
	ds_read_b128 v[132:135], v68 offset:39168
	s_waitcnt lgkmcnt(1)
	v_mfma_f32_32x32x16_bf16 v[2:17], v[104:107], v[190:193], v[2:17]
	global_load_dwordx4 v[190:193], v[214:215], off offset:-2048
	s_waitcnt vmcnt(15)
	v_mfma_f32_32x32x16_bf16 v[50:65], v[120:123], v[194:197], v[50:65]
	v_mfma_f32_32x32x16_bf16 v[34:49], v[124:127], v[194:197], v[34:49]
	v_mfma_f32_32x32x16_bf16 v[18:33], v[128:131], v[194:197], v[18:33]
	s_waitcnt lgkmcnt(0)
	v_mfma_f32_32x32x16_bf16 v[2:17], v[132:135], v[194:197], v[2:17]
	global_load_dwordx4 v[194:197], v[216:217], off offset:-2048
	ds_read_b128 v[100:103], v68 offset:1536
	ds_read_b128 v[120:123], v68 offset:768
	s_waitcnt vmcnt(15) lgkmcnt(1)
	v_mfma_f32_32x32x16_bf16 v[50:65], v[100:103], v[198:201], v[50:65]
	ds_read_b128 v[100:103], v68 offset:13824
	ds_read_b128 v[124:127], v68 offset:13056
	s_waitcnt lgkmcnt(1)
	v_mfma_f32_32x32x16_bf16 v[34:49], v[100:103], v[198:201], v[34:49]
	ds_read_b128 v[100:103], v68 offset:26112
	ds_read_b128 v[128:131], v68 offset:25344
	s_waitcnt lgkmcnt(1)
	v_mfma_f32_32x32x16_bf16 v[18:33], v[100:103], v[198:201], v[18:33]
	ds_read_b128 v[100:103], v68 offset:38400
	ds_read_b128 v[132:135], v68 offset:37632
	v_add_u32_e32 v68, 0xffffd000, v68
	s_waitcnt lgkmcnt(1)
	v_mfma_f32_32x32x16_bf16 v[2:17], v[100:103], v[198:201], v[2:17]
	global_load_dwordx4 v[198:201], v[140:141], off offset:-2048
	s_waitcnt vmcnt(15)
	v_mfma_f32_32x32x16_bf16 v[50:65], v[120:123], v[202:205], v[50:65]
	v_mfma_f32_32x32x16_bf16 v[34:49], v[124:127], v[202:205], v[34:49]
	v_mfma_f32_32x32x16_bf16 v[18:33], v[128:131], v[202:205], v[18:33]
	s_waitcnt lgkmcnt(0)
	v_mfma_f32_32x32x16_bf16 v[2:17], v[132:135], v[202:205], v[2:17]
	global_load_dwordx4 v[202:205], v[186:187], off offset:-2048
	s_waitcnt vmcnt(15)
	v_mfma_f32_32x32x16_bf16 v[50:65], v[116:119], v[206:209], v[50:65]
	v_mfma_f32_32x32x16_bf16 v[34:49], v[96:99], v[206:209], v[34:49]
	v_mfma_f32_32x32x16_bf16 v[18:33], v[108:111], v[206:209], v[18:33]
	v_mfma_f32_32x32x16_bf16 v[2:17], v[112:115], v[206:209], v[2:17]
	global_load_dwordx4 v[206:209], v[88:89], off offset:-1024
	global_load_dwordx4 v[96:99], v[214:215], off offset:-1024
	global_load_dwordx4 v[100:103], v[216:217], off offset:-1024
	global_load_dwordx4 v[104:107], v[140:141], off offset:-1024
	global_load_dwordx4 v[108:111], v[186:187], off offset:-1024
	global_load_dwordx4 v[112:115], v[88:89], off
	global_load_dwordx4 v[116:119], v[214:215], off
	global_load_dwordx4 v[120:123], v[216:217], off
	global_load_dwordx4 v[124:127], v[140:141], off
	global_load_dwordx4 v[128:131], v[186:187], off
	global_load_dwordx4 v[132:135], v[88:89], off offset:1024
	global_load_dwordx4 v[136:139], v[214:215], off offset:1024
	s_waitcnt vmcnt(25)
	v_mfma_f32_32x32x16_bf16 v[50:65], v[146:149], v[142:145], v[50:65]
	global_load_dwordx4 v[146:149], v[216:217], off offset:1024
	s_waitcnt vmcnt(25)
	v_mfma_f32_32x32x16_bf16 v[34:49], v[150:153], v[142:145], v[34:49]
	global_load_dwordx4 v[150:153], v[140:141], off offset:1024
	s_waitcnt vmcnt(25)
	v_mfma_f32_32x32x16_bf16 v[18:33], v[154:157], v[142:145], v[18:33]
	global_load_dwordx4 v[154:157], v[186:187], off offset:1024
	s_waitcnt vmcnt(25)
	v_mfma_f32_32x32x16_bf16 v[2:17], v[158:161], v[142:145], v[2:17]
	global_load_dwordx4 v[158:161], v[88:89], off offset:2048
	global_load_dwordx4 v[142:145], v[214:215], off offset:2048
	s_waitcnt vmcnt(25)
	v_mfma_f32_32x32x16_bf16 v[50:65], v[166:169], v[162:165], v[50:65]
	global_load_dwordx4 v[166:169], v[216:217], off offset:2048
	s_waitcnt vmcnt(25)
	v_mfma_f32_32x32x16_bf16 v[34:49], v[170:173], v[162:165], v[34:49]
	global_load_dwordx4 v[170:173], v[140:141], off offset:2048
	s_waitcnt vmcnt(25)
	v_mfma_f32_32x32x16_bf16 v[18:33], v[174:177], v[162:165], v[18:33]
	global_load_dwordx4 v[174:177], v[186:187], off offset:2048
	s_waitcnt vmcnt(25)
	v_mfma_f32_32x32x16_bf16 v[2:17], v[178:181], v[162:165], v[2:17]
	global_load_dwordx4 v[178:181], v[88:89], off offset:3072
	global_load_dwordx4 v[162:165], v[214:215], off offset:3072
	s_waitcnt vmcnt(25)
	v_mfma_f32_32x32x16_bf16 v[50:65], v[190:193], v[182:185], v[50:65]
	global_load_dwordx4 v[190:193], v[216:217], off offset:3072
	s_waitcnt vmcnt(25)
	v_mfma_f32_32x32x16_bf16 v[34:49], v[194:197], v[182:185], v[34:49]
	global_load_dwordx4 v[194:197], v[140:141], off offset:3072
	s_waitcnt vmcnt(25)
	v_mfma_f32_32x32x16_bf16 v[18:33], v[198:201], v[182:185], v[18:33]
	global_load_dwordx4 v[198:201], v[186:187], off offset:3072
	s_waitcnt vmcnt(25)
	v_mfma_f32_32x32x16_bf16 v[2:17], v[202:205], v[182:185], v[2:17]
	v_lshl_add_u64 v[88:89], v[88:89], 0, s[20:21]
	v_lshl_add_u64 v[214:215], v[214:215], 0, s[20:21]
	v_lshl_add_u64 v[216:217], v[216:217], 0, s[20:21]
	v_lshl_add_u64 v[140:141], v[140:141], 0, s[20:21]
	v_lshl_add_u64 v[186:187], v[186:187], 0, s[20:21]
	global_load_dwordx4 v[202:205], v[88:89], off offset:-4096
	global_load_dwordx4 v[182:185], v[214:215], off offset:-4096
	s_waitcnt vmcnt(25)
	v_mfma_f32_32x32x16_bf16 v[50:65], v[96:99], v[206:209], v[50:65]
	global_load_dwordx4 v[96:99], v[216:217], off offset:-4096
	s_waitcnt vmcnt(25)
	v_mfma_f32_32x32x16_bf16 v[34:49], v[100:103], v[206:209], v[34:49]
	global_load_dwordx4 v[100:103], v[140:141], off offset:-4096
	s_waitcnt vmcnt(25)
	v_mfma_f32_32x32x16_bf16 v[18:33], v[104:107], v[206:209], v[18:33]
	global_load_dwordx4 v[104:107], v[186:187], off offset:-4096
	s_waitcnt vmcnt(25)
; #define GAS __attribute__((address_space(1)))
; __device__ __forceinline__ void ph_s5_out(Frame& F) {
;     ...
;         { const bf16* sb = (const bf16*)(ws + WS_SIN) + (size_t)g * 9 * 16 * 512 + ((size_t)nb * 16 * 64 + lane) * 8;
;           const bf16* wc = (const bf16*)(ws + WS_WC) + (size_t)g * 1024 * 256 + (((size_t)wave * 16) * 64 + lane) * 8;
; #pragma unroll 4
;           for (int kk = 0; kk < 16; ++kk) {
;               const bf16x8_t b = *(const GAS bf16x8_t*)(sb + 512 * kk);
; #pragma unroll
;               for (int i = 0; i < 4; ++i) { const bf16x8_t a = *(const GAS bf16x8_t*)(wc + (size_t)(8 * i) * 16 * 512 + 512 * kk); acc[i] = __builtin_amdgcn_mfma_f32_32x32x16_bf16(a, b, acc[i], 0, 0, 0); }
;           } }
;         if (valid) {
	v_mfma_f32_32x32x16_bf16 v[2:17], v[108:111], v[206:209], v[2:17]
	global_load_dwordx4 v[108:111], v[88:89], off offset:-3072
	global_load_dwordx4 v[206:209], v[214:215], off offset:-3072
	s_waitcnt vmcnt(25)
	v_mfma_f32_32x32x16_bf16 v[50:65], v[116:119], v[112:115], v[50:65]
	global_load_dwordx4 v[116:119], v[216:217], off offset:-3072
	s_waitcnt vmcnt(25)
	v_mfma_f32_32x32x16_bf16 v[34:49], v[120:123], v[112:115], v[34:49]
	global_load_dwordx4 v[120:123], v[140:141], off offset:-3072
	s_waitcnt vmcnt(25)
	v_mfma_f32_32x32x16_bf16 v[18:33], v[124:127], v[112:115], v[18:33]
	global_load_dwordx4 v[124:127], v[186:187], off offset:-3072
	s_waitcnt vmcnt(25)
	v_mfma_f32_32x32x16_bf16 v[2:17], v[128:131], v[112:115], v[2:17]
	global_load_dwordx4 v[128:131], v[88:89], off offset:-2048
	global_load_dwordx4 v[112:115], v[214:215], off offset:-2048
	s_waitcnt vmcnt(25)
	v_mfma_f32_32x32x16_bf16 v[50:65], v[136:139], v[132:135], v[50:65]
	global_load_dwordx4 v[136:139], v[216:217], off offset:-2048
	s_waitcnt vmcnt(25)
	v_mfma_f32_32x32x16_bf16 v[34:49], v[146:149], v[132:135], v[34:49]
	global_load_dwordx4 v[146:149], v[140:141], off offset:-2048
	s_waitcnt vmcnt(25)
	v_mfma_f32_32x32x16_bf16 v[18:33], v[150:153], v[132:135], v[18:33]
	global_load_dwordx4 v[150:153], v[186:187], off offset:-2048
	s_waitcnt vmcnt(25)
	v_mfma_f32_32x32x16_bf16 v[2:17], v[154:157], v[132:135], v[2:17]
	global_load_dwordx4 v[154:157], v[88:89], off offset:-1024
	global_load_dwordx4 v[132:135], v[214:215], off offset:-1024
	s_waitcnt vmcnt(25)
	v_mfma_f32_32x32x16_bf16 v[50:65], v[142:145], v[158:161], v[50:65]
	global_load_dwordx4 v[142:145], v[216:217], off offset:-1024
	s_waitcnt vmcnt(25)
	v_mfma_f32_32x32x16_bf16 v[34:49], v[166:169], v[158:161], v[34:49]
	global_load_dwordx4 v[166:169], v[140:141], off offset:-1024
	s_waitcnt vmcnt(25)
	v_mfma_f32_32x32x16_bf16 v[18:33], v[170:173], v[158:161], v[18:33]
	global_load_dwordx4 v[170:173], v[186:187], off offset:-1024
	s_waitcnt vmcnt(25)
	v_mfma_f32_32x32x16_bf16 v[2:17], v[174:177], v[158:161], v[2:17]
	global_load_dwordx4 v[174:177], v[88:89], off
	global_load_dwordx4 v[158:161], v[214:215], off
	s_waitcnt vmcnt(25)
	v_mfma_f32_32x32x16_bf16 v[50:65], v[162:165], v[178:181], v[50:65]
	global_load_dwordx4 v[162:165], v[216:217], off
	s_waitcnt vmcnt(25)
	v_mfma_f32_32x32x16_bf16 v[34:49], v[190:193], v[178:181], v[34:49]
	global_load_dwordx4 v[190:193], v[140:141], off
	s_waitcnt vmcnt(25)
	v_mfma_f32_32x32x16_bf16 v[18:33], v[194:197], v[178:181], v[18:33]
	global_load_dwordx4 v[194:197], v[186:187], off
	s_waitcnt vmcnt(25)
	v_mfma_f32_32x32x16_bf16 v[2:17], v[198:201], v[178:181], v[2:17]
	global_load_dwordx4 v[198:201], v[88:89], off offset:1024
	global_load_dwordx4 v[178:181], v[214:215], off offset:1024
	s_waitcnt vmcnt(25)
	v_mfma_f32_32x32x16_bf16 v[50:65], v[182:185], v[202:205], v[50:65]
	global_load_dwordx4 v[182:185], v[216:217], off offset:1024
	s_waitcnt vmcnt(25)
	v_mfma_f32_32x32x16_bf16 v[34:49], v[96:99], v[202:205], v[34:49]
	global_load_dwordx4 v[96:99], v[140:141], off offset:1024
	s_waitcnt vmcnt(25)
	v_mfma_f32_32x32x16_bf16 v[18:33], v[100:103], v[202:205], v[18:33]
	global_load_dwordx4 v[100:103], v[186:187], off offset:1024
	s_waitcnt vmcnt(25)
	v_mfma_f32_32x32x16_bf16 v[2:17], v[104:107], v[202:205], v[2:17]
	global_load_dwordx4 v[104:107], v[88:89], off offset:2048
	global_load_dwordx4 v[202:205], v[214:215], off offset:2048
	s_waitcnt vmcnt(25)
	v_mfma_f32_32x32x16_bf16 v[50:65], v[206:209], v[108:111], v[50:65]
	global_load_dwordx4 v[206:209], v[216:217], off offset:2048
	s_waitcnt vmcnt(25)
	v_mfma_f32_32x32x16_bf16 v[34:49], v[116:119], v[108:111], v[34:49]
	global_load_dwordx4 v[116:119], v[140:141], off offset:2048
	s_waitcnt vmcnt(25)
	v_mfma_f32_32x32x16_bf16 v[18:33], v[120:123], v[108:111], v[18:33]
	global_load_dwordx4 v[120:123], v[186:187], off offset:2048
	s_waitcnt vmcnt(25)
	v_mfma_f32_32x32x16_bf16 v[2:17], v[124:127], v[108:111], v[2:17]
	global_load_dwordx4 v[124:127], v[88:89], off offset:3072
	global_load_dwordx4 v[108:111], v[214:215], off offset:3072
	s_waitcnt vmcnt(25)
	v_mfma_f32_32x32x16_bf16 v[50:65], v[112:115], v[128:131], v[50:65]
	global_load_dwordx4 v[112:115], v[216:217], off offset:3072
	s_waitcnt vmcnt(25)
	v_mfma_f32_32x32x16_bf16 v[34:49], v[136:139], v[128:131], v[34:49]
	global_load_dwordx4 v[136:139], v[140:141], off offset:3072
	s_waitcnt vmcnt(25)
	v_mfma_f32_32x32x16_bf16 v[18:33], v[146:149], v[128:131], v[18:33]
	global_load_dwordx4 v[146:149], v[186:187], off offset:3072
	s_waitcnt vmcnt(25)
	v_mfma_f32_32x32x16_bf16 v[2:17], v[150:153], v[128:131], v[2:17]
	s_waitcnt vmcnt(23)
	v_mfma_f32_32x32x16_bf16 v[50:65], v[132:135], v[154:157], v[50:65]
	s_waitcnt vmcnt(22)
	v_mfma_f32_32x32x16_bf16 v[34:49], v[142:145], v[154:157], v[34:49]
	s_waitcnt vmcnt(21)
	v_mfma_f32_32x32x16_bf16 v[18:33], v[166:169], v[154:157], v[18:33]
	s_waitcnt vmcnt(20)
	v_mfma_f32_32x32x16_bf16 v[2:17], v[170:173], v[154:157], v[2:17]
	s_waitcnt vmcnt(18)
	v_mfma_f32_32x32x16_bf16 v[50:65], v[158:161], v[174:177], v[50:65]
	s_waitcnt vmcnt(17)
	v_mfma_f32_32x32x16_bf16 v[34:49], v[162:165], v[174:177], v[34:49]
	s_waitcnt vmcnt(16)
	v_mfma_f32_32x32x16_bf16 v[18:33], v[190:193], v[174:177], v[18:33]
	s_waitcnt vmcnt(15)
	v_mfma_f32_32x32x16_bf16 v[2:17], v[194:197], v[174:177], v[2:17]
	s_waitcnt vmcnt(13)
	v_mfma_f32_32x32x16_bf16 v[50:65], v[178:181], v[198:201], v[50:65]
	s_waitcnt vmcnt(12)
	v_mfma_f32_32x32x16_bf16 v[34:49], v[182:185], v[198:201], v[34:49]
	s_waitcnt vmcnt(11)
	v_mfma_f32_32x32x16_bf16 v[18:33], v[96:99], v[198:201], v[18:33]
	s_waitcnt vmcnt(10)
	v_mfma_f32_32x32x16_bf16 v[2:17], v[100:103], v[198:201], v[2:17]
	s_waitcnt vmcnt(8)
	v_mfma_f32_32x32x16_bf16 v[50:65], v[202:205], v[104:107], v[50:65]
	s_waitcnt vmcnt(7)
	v_mfma_f32_32x32x16_bf16 v[34:49], v[206:209], v[104:107], v[34:49]
	s_waitcnt vmcnt(6)
	v_mfma_f32_32x32x16_bf16 v[18:33], v[116:119], v[104:107], v[18:33]
	s_waitcnt vmcnt(5)
	v_mfma_f32_32x32x16_bf16 v[2:17], v[120:123], v[104:107], v[2:17]
	s_waitcnt vmcnt(3)
	v_mfma_f32_32x32x16_bf16 v[50:65], v[108:111], v[124:127], v[50:65]
	s_waitcnt vmcnt(2)
	v_mfma_f32_32x32x16_bf16 v[34:49], v[112:115], v[124:127], v[34:49]
	s_waitcnt vmcnt(1)
	v_mfma_f32_32x32x16_bf16 v[18:33], v[136:139], v[124:127], v[18:33]
	s_waitcnt vmcnt(0)
	v_mfma_f32_32x32x16_bf16 v[2:17], v[146:149], v[124:127], v[2:17]
	v_lshl_or_b32 v82, s24, 5, v1
	v_cmp_gt_i32_e32 vcc, s45, v82
	s_and_saveexec_b64 s[24:25], vcc
	s_cbranch_execz .LBB0_963
; #define GAS __attribute__((address_space(1)))
; __device__ __forceinline__ unsigned pk2(float lo, float hi) { const f32x2cv v = {lo, hi}; return __builtin_bit_cast(unsigned, __builtin_convertvector(v, bf16x2cv)); }
; __device__ __forceinline__ float gelu_tanh(float x) { const float u = 0.7978845608028654f * (x + 0.044715f * x * x * x); return x * __builtin_amdgcn_rcpf(1.0f + __builtin_amdgcn_exp2f(-2.8853900817779268f * u)); }
; __device__ __forceinline__ void ph_s5_out(Frame& F) {
;     ...
;         if (valid) {
;             const float* dsk = inp(F, 24) + 16 * g;
; #pragma unroll
;             for (int i = 0; i < 4; ++i)
; #pragma unroll
;                 for (int k = 0; k < 4; ++k) { const int tloc = 2 * (wave + 8 * i) + (k >> 1), p0 = 8 * (k & 1) + 4 * hh; const size_t m = (size_t)chunk * 64 + tloc;
;                     const v2u uw = *(const GAS v2u*)((chunk < 256 ? (const bf16*)(ws + WS_UG) : (const bf16*)(ws + WS_UGC)) + ug_index(g, (int)m, p0));
;                     const float y0 = gelu_tanh(acc[i][4 * k] + dsk[p0] * bflo(uw.x)), y1 = gelu_tanh(acc[i][4 * k + 1] + dsk[p0 + 1] * bfhi(uw.x));
;                     const float y2 = gelu_tanh(acc[i][4 * k + 2] + dsk[p0 + 2] * bflo(uw.y)), y3 = gelu_tanh(acc[i][4 * k + 3] + dsk[p0 + 3] * bfhi(uw.y));
;                     v2u zw; zw.x = pk2(y0, y1); zw.y = pk2(y2, y3);
;                     *(GAS v2u*)((bf16*)(ws + WS_Z) + m * 512 + 16 * g + p0) = zw; }
	v_mov_b32_e32 v68, s46
	ds_read_b64 v[84:85], v68
	v_ashrrev_i32_e32 v83, 31, v82
	v_lshlrev_b64 v[88:89], 6, v[82:83]
	v_cmp_gt_i32_e32 vcc, s47, v82
	v_lshl_add_u64 v[102:103], v[88:89], 0, s[4:5]
	v_ashrrev_i32_e32 v83, 11, v102
	v_cndmask_b32_e32 v68, v94, v95, vcc
	v_lshl_add_u64 v[86:87], v[70:71], 0, v[68:69]
	v_ashrrev_i32_e32 v68, 6, v102
	v_add_u32_e32 v83, s30, v83
	v_mov_b32_e32 v96, s26
	v_cmp_gt_i32_e32 vcc, s47, v68
	s_lshl_b32 s28, s26, 4
	s_waitcnt lgkmcnt(0)
	v_readfirstlane_b32 s27, v84
	v_and_b32_e32 v97, 31, v68
	v_cndmask_b32_e32 v84, v96, v83, vcc
	s_ashr_i32 s29, s28, 31
	v_readfirstlane_b32 s31, v85
	v_or_b32_e32 v82, v97, v67
	v_ashrrev_i32_e32 v85, 31, v84
	v_lshlrev_b32_e32 v68, 6, v102
	s_lshl_b64 s[34:35], s[28:29], 2
	v_and_b32_e32 v68, 0xf80, v68
	v_ashrrev_i32_e32 v83, 31, v82
	v_lshlrev_b64 v[84:85], 16, v[84:85]
	v_lshl_add_u64 v[82:83], v[68:69], 0, v[82:83]
	v_lshl_add_u64 v[104:105], v[86:87], 0, v[84:85]
	s_add_u32 s26, s27, s34
	v_lshl_add_u64 v[82:83], v[82:83], 4, v[104:105]
	s_addc_u32 s27, s31, s35
	v_lshl_add_u64 v[98:99], v[188:189], 2, s[26:27]
	global_load_dwordx4 v[174:177], v[98:99], off
	global_load_dwordx4 v[178:181], v[98:99], off offset:32
	global_load_dwordx2 v[142:143], v[82:83], off
	global_load_dwordx2 v[144:145], v[82:83], off offset:512
	global_load_dwordx2 v[146:147], v[82:83], off offset:1024
	global_load_dwordx2 v[148:149], v[82:83], off offset:1536
	v_lshl_add_u64 v[82:83], v[82:83], 0, s[22:23]
	global_load_dwordx2 v[150:151], v[82:83], off
	global_load_dwordx2 v[152:153], v[82:83], off offset:512
	global_load_dwordx2 v[154:155], v[82:83], off offset:1024
	global_load_dwordx2 v[156:157], v[82:83], off offset:1536
	v_lshl_add_u64 v[82:83], v[82:83], 0, s[22:23]
	global_load_dwordx2 v[158:159], v[82:83], off
	global_load_dwordx2 v[160:161], v[82:83], off offset:512
	global_load_dwordx2 v[162:163], v[82:83], off offset:1024
	global_load_dwordx2 v[164:165], v[82:83], off offset:1536
	v_lshl_add_u64 v[82:83], v[82:83], 0, s[22:23]
	global_load_dwordx2 v[166:167], v[82:83], off
	global_load_dwordx2 v[168:169], v[82:83], off offset:512
	global_load_dwordx2 v[170:171], v[82:83], off offset:1024
	global_load_dwordx2 v[172:173], v[82:83], off offset:1536
	s_lshl_b64 s[26:27], s[28:29], 1
	s_add_u32 s26, s38, s26
	v_lshlrev_b64 v[102:103], 10, v[102:103]
	s_addc_u32 s27, s39, s27
	v_lshlrev_b64 v[84:85], 1, v[188:189]
	v_lshl_add_u64 v[102:103], s[26:27], 0, v[102:103]
	v_lshl_add_u64 v[102:103], v[102:103], 0, v[84:85]
	s_waitcnt vmcnt(15)
	v_lshlrev_b32_e32 v182, 16, v142
	v_and_b32_e32 v183, 0xffff0000, v142
	v_lshlrev_b32_e32 v184, 16, v143
	v_and_b32_e32 v185, 0xffff0000, v143
	v_pk_fma_f32 v[194:195], v[174:175], v[182:183], v[50:51]
	v_pk_fma_f32 v[196:197], v[176:177], v[184:185], v[52:53]
	v_mul_f32_e32 v190, 0x3d372713, v194
	v_mul_f32_e32 v191, 0x3d372713, v195
	v_mul_f32_e32 v192, 0x3d372713, v196
	v_mul_f32_e32 v193, 0x3d372713, v197
	v_mul_f32_e32 v190, v194, v190
	v_mul_f32_e32 v191, v195, v191
	v_mul_f32_e32 v192, v196, v192
	v_mul_f32_e32 v193, v197, v193
	v_fma_f32 v190, v194, v190, v194
	v_fma_f32 v191, v195, v191, v195
	v_fma_f32 v192, v196, v192, v196
	v_fma_f32 v193, v197, v193, v197
	v_mul_f32_e32 v190, 0x3f4c422a, v190
	v_mul_f32_e32 v191, 0x3f4c422a, v191
	v_mul_f32_e32 v192, 0x3f4c422a, v192
	v_mul_f32_e32 v193, 0x3f4c422a, v193
	v_mul_f32_e32 v190, 0xc038aa3b, v190
	v_mul_f32_e32 v191, 0xc038aa3b, v191
	v_mul_f32_e32 v192, 0xc038aa3b, v192
	v_mul_f32_e32 v193, 0xc038aa3b, v193
	v_exp_f32_e32 v190, v190
	v_exp_f32_e32 v191, v191
	v_exp_f32_e32 v192, v192
	v_exp_f32_e32 v193, v193
	v_add_f32_e32 v190, 1.0, v190
	v_add_f32_e32 v191, 1.0, v191
	v_add_f32_e32 v192, 1.0, v192
	v_add_f32_e32 v193, 1.0, v193
	v_rcp_f32_e32 v190, v190
	v_rcp_f32_e32 v191, v191
	v_rcp_f32_e32 v192, v192
	v_rcp_f32_e32 v193, v193
	v_pk_mul_f32 v[194:195], v[194:195], v[190:191]
	v_pk_mul_f32 v[196:197], v[196:197], v[192:193]
	v_cvt_pk_bf16_f32 v194, v194, v195
	v_cvt_pk_bf16_f32 v195, v196, v197
	global_store_dwordx2 v[102:103], v[194:195], off
	s_waitcnt vmcnt(15)
	v_lshlrev_b32_e32 v182, 16, v144
	v_and_b32_e32 v183, 0xffff0000, v144
	v_lshlrev_b32_e32 v184, 16, v145
	v_and_b32_e32 v185, 0xffff0000, v145
	v_pk_fma_f32 v[194:195], v[178:179], v[182:183], v[54:55]
	v_pk_fma_f32 v[196:197], v[180:181], v[184:185], v[56:57]
	v_mul_f32_e32 v190, 0x3d372713, v194
	v_mul_f32_e32 v191, 0x3d372713, v195
	v_mul_f32_e32 v192, 0x3d372713, v196
	v_mul_f32_e32 v193, 0x3d372713, v197
	v_mul_f32_e32 v190, v194, v190
	v_mul_f32_e32 v191, v195, v191
	v_mul_f32_e32 v192, v196, v192
	v_mul_f32_e32 v193, v197, v193
	v_fma_f32 v190, v194, v190, v194
	v_fma_f32 v191, v195, v191, v195
	v_fma_f32 v192, v196, v192, v196
	v_fma_f32 v193, v197, v193, v197
	v_mul_f32_e32 v190, 0x3f4c422a, v190
	v_mul_f32_e32 v191, 0x3f4c422a, v191
	v_mul_f32_e32 v192, 0x3f4c422a, v192
	v_mul_f32_e32 v193, 0x3f4c422a, v193
	v_mul_f32_e32 v190, 0xc038aa3b, v190
	v_mul_f32_e32 v191, 0xc038aa3b, v191
	v_mul_f32_e32 v192, 0xc038aa3b, v192
	v_mul_f32_e32 v193, 0xc038aa3b, v193
	v_exp_f32_e32 v190, v190
	v_exp_f32_e32 v191, v191
	v_exp_f32_e32 v192, v192
	v_exp_f32_e32 v193, v193
	v_add_f32_e32 v190, 1.0, v190
	v_add_f32_e32 v191, 1.0, v191
	v_add_f32_e32 v192, 1.0, v192
	v_add_f32_e32 v193, 1.0, v193
	v_rcp_f32_e32 v190, v190
	v_rcp_f32_e32 v191, v191
	v_rcp_f32_e32 v192, v192
	v_rcp_f32_e32 v193, v193
	v_pk_mul_f32 v[194:195], v[194:195], v[190:191]
	v_pk_mul_f32 v[196:197], v[196:197], v[192:193]
	v_cvt_pk_bf16_f32 v194, v194, v195
	v_cvt_pk_bf16_f32 v195, v196, v197
	global_store_dwordx2 v[102:103], v[194:195], off offset:16
	s_waitcnt vmcnt(15)
; #define GAS __attribute__((address_space(1)))
; __device__ __forceinline__ unsigned pk2(float lo, float hi) { const f32x2cv v = {lo, hi}; return __builtin_bit_cast(unsigned, __builtin_convertvector(v, bf16x2cv)); }
; __device__ __forceinline__ float gelu_tanh(float x) { const float u = 0.7978845608028654f * (x + 0.044715f * x * x * x); return x * __builtin_amdgcn_rcpf(1.0f + __builtin_amdgcn_exp2f(-2.8853900817779268f * u)); }
; __device__ __forceinline__ void ph_s5_out(Frame& F) {
;     ...
;                 for (int k = 0; k < 4; ++k) { const int tloc = 2 * (wave + 8 * i) + (k >> 1), p0 = 8 * (k & 1) + 4 * hh; const size_t m = (size_t)chunk * 64 + tloc;
;                     const v2u uw = *(const GAS v2u*)((chunk < 256 ? (const bf16*)(ws + WS_UG) : (const bf16*)(ws + WS_UGC)) + ug_index(g, (int)m, p0));
;                     const float y0 = gelu_tanh(acc[i][4 * k] + dsk[p0] * bflo(uw.x)), y1 = gelu_tanh(acc[i][4 * k + 1] + dsk[p0 + 1] * bfhi(uw.x));
;                     const float y2 = gelu_tanh(acc[i][4 * k + 2] + dsk[p0 + 2] * bflo(uw.y)), y3 = gelu_tanh(acc[i][4 * k + 3] + dsk[p0 + 3] * bfhi(uw.y));
;                     v2u zw; zw.x = pk2(y0, y1); zw.y = pk2(y2, y3);
;                     *(GAS v2u*)((bf16*)(ws + WS_Z) + m * 512 + 16 * g + p0) = zw; }
	v_lshlrev_b32_e32 v182, 16, v146
	v_and_b32_e32 v183, 0xffff0000, v146
	v_lshlrev_b32_e32 v184, 16, v147
	v_and_b32_e32 v185, 0xffff0000, v147
	v_pk_fma_f32 v[194:195], v[174:175], v[182:183], v[58:59]
	v_pk_fma_f32 v[196:197], v[176:177], v[184:185], v[60:61]
	v_mul_f32_e32 v190, 0x3d372713, v194
	v_mul_f32_e32 v191, 0x3d372713, v195
	v_mul_f32_e32 v192, 0x3d372713, v196
	v_mul_f32_e32 v193, 0x3d372713, v197
	v_mul_f32_e32 v190, v194, v190
	v_mul_f32_e32 v191, v195, v191
	v_mul_f32_e32 v192, v196, v192
	v_mul_f32_e32 v193, v197, v193
	v_fma_f32 v190, v194, v190, v194
	v_fma_f32 v191, v195, v191, v195
	v_fma_f32 v192, v196, v192, v196
	v_fma_f32 v193, v197, v193, v197
	v_mul_f32_e32 v190, 0x3f4c422a, v190
	v_mul_f32_e32 v191, 0x3f4c422a, v191
	v_mul_f32_e32 v192, 0x3f4c422a, v192
	v_mul_f32_e32 v193, 0x3f4c422a, v193
	v_mul_f32_e32 v190, 0xc038aa3b, v190
	v_mul_f32_e32 v191, 0xc038aa3b, v191
	v_mul_f32_e32 v192, 0xc038aa3b, v192
	v_mul_f32_e32 v193, 0xc038aa3b, v193
	v_exp_f32_e32 v190, v190
	v_exp_f32_e32 v191, v191
	v_exp_f32_e32 v192, v192
	v_exp_f32_e32 v193, v193
	v_add_f32_e32 v190, 1.0, v190
	v_add_f32_e32 v191, 1.0, v191
	v_add_f32_e32 v192, 1.0, v192
	v_add_f32_e32 v193, 1.0, v193
	v_rcp_f32_e32 v190, v190
	v_rcp_f32_e32 v191, v191
	v_rcp_f32_e32 v192, v192
	v_rcp_f32_e32 v193, v193
	v_pk_mul_f32 v[194:195], v[194:195], v[190:191]
	v_pk_mul_f32 v[196:197], v[196:197], v[192:193]
	v_cvt_pk_bf16_f32 v194, v194, v195
	v_cvt_pk_bf16_f32 v195, v196, v197
	global_store_dwordx2 v[102:103], v[194:195], off offset:1024
	s_waitcnt vmcnt(15)
	v_lshlrev_b32_e32 v182, 16, v148
	v_and_b32_e32 v183, 0xffff0000, v148
	v_lshlrev_b32_e32 v184, 16, v149
	v_and_b32_e32 v185, 0xffff0000, v149
	v_pk_fma_f32 v[194:195], v[178:179], v[182:183], v[62:63]
	v_pk_fma_f32 v[196:197], v[180:181], v[184:185], v[64:65]
	v_mul_f32_e32 v190, 0x3d372713, v194
	v_mul_f32_e32 v191, 0x3d372713, v195
	v_mul_f32_e32 v192, 0x3d372713, v196
	v_mul_f32_e32 v193, 0x3d372713, v197
	v_mul_f32_e32 v190, v194, v190
	v_mul_f32_e32 v191, v195, v191
	v_mul_f32_e32 v192, v196, v192
	v_mul_f32_e32 v193, v197, v193
	v_fma_f32 v190, v194, v190, v194
	v_fma_f32 v191, v195, v191, v195
	v_fma_f32 v192, v196, v192, v196
	v_fma_f32 v193, v197, v193, v197
	v_mul_f32_e32 v190, 0x3f4c422a, v190
	v_mul_f32_e32 v191, 0x3f4c422a, v191
	v_mul_f32_e32 v192, 0x3f4c422a, v192
	v_mul_f32_e32 v193, 0x3f4c422a, v193
	v_mul_f32_e32 v190, 0xc038aa3b, v190
	v_mul_f32_e32 v191, 0xc038aa3b, v191
	v_mul_f32_e32 v192, 0xc038aa3b, v192
	v_mul_f32_e32 v193, 0xc038aa3b, v193
	v_exp_f32_e32 v190, v190
	v_exp_f32_e32 v191, v191
	v_exp_f32_e32 v192, v192
	v_exp_f32_e32 v193, v193
	v_add_f32_e32 v190, 1.0, v190
	v_add_f32_e32 v191, 1.0, v191
	v_add_f32_e32 v192, 1.0, v192
	v_add_f32_e32 v193, 1.0, v193
	v_rcp_f32_e32 v190, v190
	v_rcp_f32_e32 v191, v191
	v_rcp_f32_e32 v192, v192
	v_rcp_f32_e32 v193, v193
	v_pk_mul_f32 v[194:195], v[194:195], v[190:191]
	v_pk_mul_f32 v[196:197], v[196:197], v[192:193]
	v_cvt_pk_bf16_f32 v194, v194, v195
	v_cvt_pk_bf16_f32 v195, v196, v197
	global_store_dwordx2 v[102:103], v[194:195], off offset:1040
	v_lshl_add_u64 v[102:103], v[102:103], 0, s[22:23]
	s_waitcnt vmcnt(15)
	v_lshlrev_b32_e32 v182, 16, v150
	v_and_b32_e32 v183, 0xffff0000, v150
	v_lshlrev_b32_e32 v184, 16, v151
	v_and_b32_e32 v185, 0xffff0000, v151
	v_pk_fma_f32 v[194:195], v[174:175], v[182:183], v[34:35]
	v_pk_fma_f32 v[196:197], v[176:177], v[184:185], v[36:37]
	v_mul_f32_e32 v190, 0x3d372713, v194
	v_mul_f32_e32 v191, 0x3d372713, v195
	v_mul_f32_e32 v192, 0x3d372713, v196
	v_mul_f32_e32 v193, 0x3d372713, v197
	v_mul_f32_e32 v190, v194, v190
	v_mul_f32_e32 v191, v195, v191
	v_mul_f32_e32 v192, v196, v192
	v_mul_f32_e32 v193, v197, v193
	v_fma_f32 v190, v194, v190, v194
	v_fma_f32 v191, v195, v191, v195
	v_fma_f32 v192, v196, v192, v196
	v_fma_f32 v193, v197, v193, v197
	v_mul_f32_e32 v190, 0x3f4c422a, v190
	v_mul_f32_e32 v191, 0x3f4c422a, v191
	v_mul_f32_e32 v192, 0x3f4c422a, v192
	v_mul_f32_e32 v193, 0x3f4c422a, v193
	v_mul_f32_e32 v190, 0xc038aa3b, v190
	v_mul_f32_e32 v191, 0xc038aa3b, v191
	v_mul_f32_e32 v192, 0xc038aa3b, v192
	v_mul_f32_e32 v193, 0xc038aa3b, v193
	v_exp_f32_e32 v190, v190
	v_exp_f32_e32 v191, v191
	v_exp_f32_e32 v192, v192
	v_exp_f32_e32 v193, v193
	v_add_f32_e32 v190, 1.0, v190
	v_add_f32_e32 v191, 1.0, v191
	v_add_f32_e32 v192, 1.0, v192
	v_add_f32_e32 v193, 1.0, v193
	v_rcp_f32_e32 v190, v190
	v_rcp_f32_e32 v191, v191
	v_rcp_f32_e32 v192, v192
	v_rcp_f32_e32 v193, v193
	v_pk_mul_f32 v[194:195], v[194:195], v[190:191]
	v_pk_mul_f32 v[196:197], v[196:197], v[192:193]
	v_cvt_pk_bf16_f32 v194, v194, v195
	v_cvt_pk_bf16_f32 v195, v196, v197
	global_store_dwordx2 v[102:103], v[194:195], off
	s_waitcnt vmcnt(15)
	v_lshlrev_b32_e32 v182, 16, v152
	v_and_b32_e32 v183, 0xffff0000, v152
	v_lshlrev_b32_e32 v184, 16, v153
	v_and_b32_e32 v185, 0xffff0000, v153
	v_pk_fma_f32 v[194:195], v[178:179], v[182:183], v[38:39]
	v_pk_fma_f32 v[196:197], v[180:181], v[184:185], v[40:41]
	v_mul_f32_e32 v190, 0x3d372713, v194
	v_mul_f32_e32 v191, 0x3d372713, v195
	v_mul_f32_e32 v192, 0x3d372713, v196
	v_mul_f32_e32 v193, 0x3d372713, v197
	v_mul_f32_e32 v190, v194, v190
	v_mul_f32_e32 v191, v195, v191
	v_mul_f32_e32 v192, v196, v192
	v_mul_f32_e32 v193, v197, v193
	v_fma_f32 v190, v194, v190, v194
	v_fma_f32 v191, v195, v191, v195
	v_fma_f32 v192, v196, v192, v196
	v_fma_f32 v193, v197, v193, v197
	v_mul_f32_e32 v190, 0x3f4c422a, v190
	v_mul_f32_e32 v191, 0x3f4c422a, v191
	v_mul_f32_e32 v192, 0x3f4c422a, v192
	v_mul_f32_e32 v193, 0x3f4c422a, v193
	v_mul_f32_e32 v190, 0xc038aa3b, v190
	v_mul_f32_e32 v191, 0xc038aa3b, v191
	v_mul_f32_e32 v192, 0xc038aa3b, v192
	v_mul_f32_e32 v193, 0xc038aa3b, v193
	v_exp_f32_e32 v190, v190
	v_exp_f32_e32 v191, v191
	v_exp_f32_e32 v192, v192
	v_exp_f32_e32 v193, v193
	v_add_f32_e32 v190, 1.0, v190
	v_add_f32_e32 v191, 1.0, v191
	v_add_f32_e32 v192, 1.0, v192
	v_add_f32_e32 v193, 1.0, v193
	v_rcp_f32_e32 v190, v190
	v_rcp_f32_e32 v191, v191
	v_rcp_f32_e32 v192, v192
	v_rcp_f32_e32 v193, v193
	v_pk_mul_f32 v[194:195], v[194:195], v[190:191]
	v_pk_mul_f32 v[196:197], v[196:197], v[192:193]
	v_cvt_pk_bf16_f32 v194, v194, v195
	v_cvt_pk_bf16_f32 v195, v196, v197
	global_store_dwordx2 v[102:103], v[194:195], off offset:16
	s_waitcnt vmcnt(15)
; #define GAS __attribute__((address_space(1)))
; __device__ __forceinline__ unsigned pk2(float lo, float hi) { const f32x2cv v = {lo, hi}; return __builtin_bit_cast(unsigned, __builtin_convertvector(v, bf16x2cv)); }
; __device__ __forceinline__ float gelu_tanh(float x) { const float u = 0.7978845608028654f * (x + 0.044715f * x * x * x); return x * __builtin_amdgcn_rcpf(1.0f + __builtin_amdgcn_exp2f(-2.8853900817779268f * u)); }
; __device__ __forceinline__ void ph_s5_out(Frame& F) {
;     ...
;                 for (int k = 0; k < 4; ++k) { const int tloc = 2 * (wave + 8 * i) + (k >> 1), p0 = 8 * (k & 1) + 4 * hh; const size_t m = (size_t)chunk * 64 + tloc;
;                     const v2u uw = *(const GAS v2u*)((chunk < 256 ? (const bf16*)(ws + WS_UG) : (const bf16*)(ws + WS_UGC)) + ug_index(g, (int)m, p0));
;                     const float y0 = gelu_tanh(acc[i][4 * k] + dsk[p0] * bflo(uw.x)), y1 = gelu_tanh(acc[i][4 * k + 1] + dsk[p0 + 1] * bfhi(uw.x));
;                     const float y2 = gelu_tanh(acc[i][4 * k + 2] + dsk[p0 + 2] * bflo(uw.y)), y3 = gelu_tanh(acc[i][4 * k + 3] + dsk[p0 + 3] * bfhi(uw.y));
;                     v2u zw; zw.x = pk2(y0, y1); zw.y = pk2(y2, y3);
;                     *(GAS v2u*)((bf16*)(ws + WS_Z) + m * 512 + 16 * g + p0) = zw; }
	v_lshlrev_b32_e32 v182, 16, v154
	v_and_b32_e32 v183, 0xffff0000, v154
	v_lshlrev_b32_e32 v184, 16, v155
	v_and_b32_e32 v185, 0xffff0000, v155
	v_pk_fma_f32 v[194:195], v[174:175], v[182:183], v[42:43]
	v_pk_fma_f32 v[196:197], v[176:177], v[184:185], v[44:45]
	v_mul_f32_e32 v190, 0x3d372713, v194
	v_mul_f32_e32 v191, 0x3d372713, v195
	v_mul_f32_e32 v192, 0x3d372713, v196
	v_mul_f32_e32 v193, 0x3d372713, v197
	v_mul_f32_e32 v190, v194, v190
	v_mul_f32_e32 v191, v195, v191
	v_mul_f32_e32 v192, v196, v192
	v_mul_f32_e32 v193, v197, v193
	v_fma_f32 v190, v194, v190, v194
	v_fma_f32 v191, v195, v191, v195
	v_fma_f32 v192, v196, v192, v196
	v_fma_f32 v193, v197, v193, v197
	v_mul_f32_e32 v190, 0x3f4c422a, v190
	v_mul_f32_e32 v191, 0x3f4c422a, v191
	v_mul_f32_e32 v192, 0x3f4c422a, v192
	v_mul_f32_e32 v193, 0x3f4c422a, v193
	v_mul_f32_e32 v190, 0xc038aa3b, v190
	v_mul_f32_e32 v191, 0xc038aa3b, v191
	v_mul_f32_e32 v192, 0xc038aa3b, v192
	v_mul_f32_e32 v193, 0xc038aa3b, v193
	v_exp_f32_e32 v190, v190
	v_exp_f32_e32 v191, v191
	v_exp_f32_e32 v192, v192
	v_exp_f32_e32 v193, v193
	v_add_f32_e32 v190, 1.0, v190
	v_add_f32_e32 v191, 1.0, v191
	v_add_f32_e32 v192, 1.0, v192
	v_add_f32_e32 v193, 1.0, v193
	v_rcp_f32_e32 v190, v190
	v_rcp_f32_e32 v191, v191
	v_rcp_f32_e32 v192, v192
	v_rcp_f32_e32 v193, v193
	v_pk_mul_f32 v[194:195], v[194:195], v[190:191]
	v_pk_mul_f32 v[196:197], v[196:197], v[192:193]
	v_cvt_pk_bf16_f32 v194, v194, v195
	v_cvt_pk_bf16_f32 v195, v196, v197
	global_store_dwordx2 v[102:103], v[194:195], off offset:1024
	s_waitcnt vmcnt(15)
	v_lshlrev_b32_e32 v182, 16, v156
	v_and_b32_e32 v183, 0xffff0000, v156
	v_lshlrev_b32_e32 v184, 16, v157
	v_and_b32_e32 v185, 0xffff0000, v157
	v_pk_fma_f32 v[194:195], v[178:179], v[182:183], v[46:47]
	v_pk_fma_f32 v[196:197], v[180:181], v[184:185], v[48:49]
	v_mul_f32_e32 v190, 0x3d372713, v194
	v_mul_f32_e32 v191, 0x3d372713, v195
	v_mul_f32_e32 v192, 0x3d372713, v196
	v_mul_f32_e32 v193, 0x3d372713, v197
	v_mul_f32_e32 v190, v194, v190
	v_mul_f32_e32 v191, v195, v191
	v_mul_f32_e32 v192, v196, v192
	v_mul_f32_e32 v193, v197, v193
	v_fma_f32 v190, v194, v190, v194
	v_fma_f32 v191, v195, v191, v195
	v_fma_f32 v192, v196, v192, v196
	v_fma_f32 v193, v197, v193, v197
	v_mul_f32_e32 v190, 0x3f4c422a, v190
	v_mul_f32_e32 v191, 0x3f4c422a, v191
	v_mul_f32_e32 v192, 0x3f4c422a, v192
	v_mul_f32_e32 v193, 0x3f4c422a, v193
	v_mul_f32_e32 v190, 0xc038aa3b, v190
	v_mul_f32_e32 v191, 0xc038aa3b, v191
	v_mul_f32_e32 v192, 0xc038aa3b, v192
	v_mul_f32_e32 v193, 0xc038aa3b, v193
	v_exp_f32_e32 v190, v190
	v_exp_f32_e32 v191, v191
	v_exp_f32_e32 v192, v192
	v_exp_f32_e32 v193, v193
	v_add_f32_e32 v190, 1.0, v190
	v_add_f32_e32 v191, 1.0, v191
	v_add_f32_e32 v192, 1.0, v192
	v_add_f32_e32 v193, 1.0, v193
	v_rcp_f32_e32 v190, v190
	v_rcp_f32_e32 v191, v191
	v_rcp_f32_e32 v192, v192
	v_rcp_f32_e32 v193, v193
	v_pk_mul_f32 v[194:195], v[194:195], v[190:191]
	v_pk_mul_f32 v[196:197], v[196:197], v[192:193]
	v_cvt_pk_bf16_f32 v194, v194, v195
	v_cvt_pk_bf16_f32 v195, v196, v197
	global_store_dwordx2 v[102:103], v[194:195], off offset:1040
	v_lshl_add_u64 v[102:103], v[102:103], 0, s[22:23]
	s_waitcnt vmcnt(15)
	v_lshlrev_b32_e32 v182, 16, v158
	v_and_b32_e32 v183, 0xffff0000, v158
	v_lshlrev_b32_e32 v184, 16, v159
	v_and_b32_e32 v185, 0xffff0000, v159
	v_pk_fma_f32 v[194:195], v[174:175], v[182:183], v[18:19]
	v_pk_fma_f32 v[196:197], v[176:177], v[184:185], v[20:21]
	v_mul_f32_e32 v190, 0x3d372713, v194
	v_mul_f32_e32 v191, 0x3d372713, v195
	v_mul_f32_e32 v192, 0x3d372713, v196
	v_mul_f32_e32 v193, 0x3d372713, v197
	v_mul_f32_e32 v190, v194, v190
	v_mul_f32_e32 v191, v195, v191
	v_mul_f32_e32 v192, v196, v192
	v_mul_f32_e32 v193, v197, v193
	v_fma_f32 v190, v194, v190, v194
	v_fma_f32 v191, v195, v191, v195
	v_fma_f32 v192, v196, v192, v196
	v_fma_f32 v193, v197, v193, v197
	v_mul_f32_e32 v190, 0x3f4c422a, v190
	v_mul_f32_e32 v191, 0x3f4c422a, v191
	v_mul_f32_e32 v192, 0x3f4c422a, v192
	v_mul_f32_e32 v193, 0x3f4c422a, v193
	v_mul_f32_e32 v190, 0xc038aa3b, v190
	v_mul_f32_e32 v191, 0xc038aa3b, v191
	v_mul_f32_e32 v192, 0xc038aa3b, v192
	v_mul_f32_e32 v193, 0xc038aa3b, v193
	v_exp_f32_e32 v190, v190
	v_exp_f32_e32 v191, v191
	v_exp_f32_e32 v192, v192
	v_exp_f32_e32 v193, v193
	v_add_f32_e32 v190, 1.0, v190
	v_add_f32_e32 v191, 1.0, v191
	v_add_f32_e32 v192, 1.0, v192
	v_add_f32_e32 v193, 1.0, v193
	v_rcp_f32_e32 v190, v190
	v_rcp_f32_e32 v191, v191
	v_rcp_f32_e32 v192, v192
	v_rcp_f32_e32 v193, v193
	v_pk_mul_f32 v[194:195], v[194:195], v[190:191]
	v_pk_mul_f32 v[196:197], v[196:197], v[192:193]
	v_cvt_pk_bf16_f32 v194, v194, v195
	v_cvt_pk_bf16_f32 v195, v196, v197
	global_store_dwordx2 v[102:103], v[194:195], off
	s_waitcnt vmcnt(15)
	v_lshlrev_b32_e32 v182, 16, v160
	v_and_b32_e32 v183, 0xffff0000, v160
	v_lshlrev_b32_e32 v184, 16, v161
	v_and_b32_e32 v185, 0xffff0000, v161
	v_pk_fma_f32 v[194:195], v[178:179], v[182:183], v[22:23]
	v_pk_fma_f32 v[196:197], v[180:181], v[184:185], v[24:25]
	v_mul_f32_e32 v190, 0x3d372713, v194
	v_mul_f32_e32 v191, 0x3d372713, v195
	v_mul_f32_e32 v192, 0x3d372713, v196
	v_mul_f32_e32 v193, 0x3d372713, v197
	v_mul_f32_e32 v190, v194, v190
	v_mul_f32_e32 v191, v195, v191
	v_mul_f32_e32 v192, v196, v192
	v_mul_f32_e32 v193, v197, v193
	v_fma_f32 v190, v194, v190, v194
	v_fma_f32 v191, v195, v191, v195
	v_fma_f32 v192, v196, v192, v196
	v_fma_f32 v193, v197, v193, v197
	v_mul_f32_e32 v190, 0x3f4c422a, v190
	v_mul_f32_e32 v191, 0x3f4c422a, v191
	v_mul_f32_e32 v192, 0x3f4c422a, v192
	v_mul_f32_e32 v193, 0x3f4c422a, v193
	v_mul_f32_e32 v190, 0xc038aa3b, v190
	v_mul_f32_e32 v191, 0xc038aa3b, v191
	v_mul_f32_e32 v192, 0xc038aa3b, v192
	v_mul_f32_e32 v193, 0xc038aa3b, v193
	v_exp_f32_e32 v190, v190
	v_exp_f32_e32 v191, v191
	v_exp_f32_e32 v192, v192
	v_exp_f32_e32 v193, v193
	v_add_f32_e32 v190, 1.0, v190
	v_add_f32_e32 v191, 1.0, v191
	v_add_f32_e32 v192, 1.0, v192
	v_add_f32_e32 v193, 1.0, v193
	v_rcp_f32_e32 v190, v190
	v_rcp_f32_e32 v191, v191
	v_rcp_f32_e32 v192, v192
	v_rcp_f32_e32 v193, v193
	v_pk_mul_f32 v[194:195], v[194:195], v[190:191]
	v_pk_mul_f32 v[196:197], v[196:197], v[192:193]
	v_cvt_pk_bf16_f32 v194, v194, v195
	v_cvt_pk_bf16_f32 v195, v196, v197
	global_store_dwordx2 v[102:103], v[194:195], off offset:16
	s_waitcnt vmcnt(15)
; #define GAS __attribute__((address_space(1)))
; __device__ __forceinline__ unsigned pk2(float lo, float hi) { const f32x2cv v = {lo, hi}; return __builtin_bit_cast(unsigned, __builtin_convertvector(v, bf16x2cv)); }
; __device__ __forceinline__ float gelu_tanh(float x) { const float u = 0.7978845608028654f * (x + 0.044715f * x * x * x); return x * __builtin_amdgcn_rcpf(1.0f + __builtin_amdgcn_exp2f(-2.8853900817779268f * u)); }
; __device__ __forceinline__ void ph_s5_out(Frame& F) {
;     ...
;                 for (int k = 0; k < 4; ++k) { const int tloc = 2 * (wave + 8 * i) + (k >> 1), p0 = 8 * (k & 1) + 4 * hh; const size_t m = (size_t)chunk * 64 + tloc;
;                     const v2u uw = *(const GAS v2u*)((chunk < 256 ? (const bf16*)(ws + WS_UG) : (const bf16*)(ws + WS_UGC)) + ug_index(g, (int)m, p0));
;                     const float y0 = gelu_tanh(acc[i][4 * k] + dsk[p0] * bflo(uw.x)), y1 = gelu_tanh(acc[i][4 * k + 1] + dsk[p0 + 1] * bfhi(uw.x));
;                     const float y2 = gelu_tanh(acc[i][4 * k + 2] + dsk[p0 + 2] * bflo(uw.y)), y3 = gelu_tanh(acc[i][4 * k + 3] + dsk[p0 + 3] * bfhi(uw.y));
;                     v2u zw; zw.x = pk2(y0, y1); zw.y = pk2(y2, y3);
;                     *(GAS v2u*)((bf16*)(ws + WS_Z) + m * 512 + 16 * g + p0) = zw; }
	v_lshlrev_b32_e32 v182, 16, v162
	v_and_b32_e32 v183, 0xffff0000, v162
	v_lshlrev_b32_e32 v184, 16, v163
	v_and_b32_e32 v185, 0xffff0000, v163
	v_pk_fma_f32 v[194:195], v[174:175], v[182:183], v[26:27]
	v_pk_fma_f32 v[196:197], v[176:177], v[184:185], v[28:29]
	v_mul_f32_e32 v190, 0x3d372713, v194
	v_mul_f32_e32 v191, 0x3d372713, v195
	v_mul_f32_e32 v192, 0x3d372713, v196
	v_mul_f32_e32 v193, 0x3d372713, v197
	v_mul_f32_e32 v190, v194, v190
	v_mul_f32_e32 v191, v195, v191
	v_mul_f32_e32 v192, v196, v192
	v_mul_f32_e32 v193, v197, v193
	v_fma_f32 v190, v194, v190, v194
	v_fma_f32 v191, v195, v191, v195
	v_fma_f32 v192, v196, v192, v196
	v_fma_f32 v193, v197, v193, v197
	v_mul_f32_e32 v190, 0x3f4c422a, v190
	v_mul_f32_e32 v191, 0x3f4c422a, v191
	v_mul_f32_e32 v192, 0x3f4c422a, v192
	v_mul_f32_e32 v193, 0x3f4c422a, v193
	v_mul_f32_e32 v190, 0xc038aa3b, v190
	v_mul_f32_e32 v191, 0xc038aa3b, v191
	v_mul_f32_e32 v192, 0xc038aa3b, v192
	v_mul_f32_e32 v193, 0xc038aa3b, v193
	v_exp_f32_e32 v190, v190
	v_exp_f32_e32 v191, v191
	v_exp_f32_e32 v192, v192
	v_exp_f32_e32 v193, v193
	v_add_f32_e32 v190, 1.0, v190
	v_add_f32_e32 v191, 1.0, v191
	v_add_f32_e32 v192, 1.0, v192
	v_add_f32_e32 v193, 1.0, v193
	v_rcp_f32_e32 v190, v190
	v_rcp_f32_e32 v191, v191
	v_rcp_f32_e32 v192, v192
	v_rcp_f32_e32 v193, v193
	v_pk_mul_f32 v[194:195], v[194:195], v[190:191]
	v_pk_mul_f32 v[196:197], v[196:197], v[192:193]
	v_cvt_pk_bf16_f32 v194, v194, v195
	v_cvt_pk_bf16_f32 v195, v196, v197
	global_store_dwordx2 v[102:103], v[194:195], off offset:1024
	s_waitcnt vmcnt(15)
	v_lshlrev_b32_e32 v182, 16, v164
	v_and_b32_e32 v183, 0xffff0000, v164
	v_lshlrev_b32_e32 v184, 16, v165
	v_and_b32_e32 v185, 0xffff0000, v165
	v_pk_fma_f32 v[194:195], v[178:179], v[182:183], v[30:31]
	v_pk_fma_f32 v[196:197], v[180:181], v[184:185], v[32:33]
	v_mul_f32_e32 v190, 0x3d372713, v194
	v_mul_f32_e32 v191, 0x3d372713, v195
	v_mul_f32_e32 v192, 0x3d372713, v196
	v_mul_f32_e32 v193, 0x3d372713, v197
	v_mul_f32_e32 v190, v194, v190
	v_mul_f32_e32 v191, v195, v191
	v_mul_f32_e32 v192, v196, v192
	v_mul_f32_e32 v193, v197, v193
	v_fma_f32 v190, v194, v190, v194
	v_fma_f32 v191, v195, v191, v195
	v_fma_f32 v192, v196, v192, v196
	v_fma_f32 v193, v197, v193, v197
	v_mul_f32_e32 v190, 0x3f4c422a, v190
	v_mul_f32_e32 v191, 0x3f4c422a, v191
	v_mul_f32_e32 v192, 0x3f4c422a, v192
	v_mul_f32_e32 v193, 0x3f4c422a, v193
	v_mul_f32_e32 v190, 0xc038aa3b, v190
	v_mul_f32_e32 v191, 0xc038aa3b, v191
	v_mul_f32_e32 v192, 0xc038aa3b, v192
	v_mul_f32_e32 v193, 0xc038aa3b, v193
	v_exp_f32_e32 v190, v190
	v_exp_f32_e32 v191, v191
	v_exp_f32_e32 v192, v192
	v_exp_f32_e32 v193, v193
	v_add_f32_e32 v190, 1.0, v190
	v_add_f32_e32 v191, 1.0, v191
	v_add_f32_e32 v192, 1.0, v192
	v_add_f32_e32 v193, 1.0, v193
	v_rcp_f32_e32 v190, v190
	v_rcp_f32_e32 v191, v191
	v_rcp_f32_e32 v192, v192
	v_rcp_f32_e32 v193, v193
	v_pk_mul_f32 v[194:195], v[194:195], v[190:191]
	v_pk_mul_f32 v[196:197], v[196:197], v[192:193]
	v_cvt_pk_bf16_f32 v194, v194, v195
	v_cvt_pk_bf16_f32 v195, v196, v197
	global_store_dwordx2 v[102:103], v[194:195], off offset:1040
	v_lshl_add_u64 v[102:103], v[102:103], 0, s[22:23]
	s_waitcnt vmcnt(15)
	v_lshlrev_b32_e32 v182, 16, v166
	v_and_b32_e32 v183, 0xffff0000, v166
	v_lshlrev_b32_e32 v184, 16, v167
	v_and_b32_e32 v185, 0xffff0000, v167
	v_pk_fma_f32 v[194:195], v[174:175], v[182:183], v[2:3]
	v_pk_fma_f32 v[196:197], v[176:177], v[184:185], v[4:5]
	v_mul_f32_e32 v190, 0x3d372713, v194
	v_mul_f32_e32 v191, 0x3d372713, v195
	v_mul_f32_e32 v192, 0x3d372713, v196
	v_mul_f32_e32 v193, 0x3d372713, v197
	v_mul_f32_e32 v190, v194, v190
	v_mul_f32_e32 v191, v195, v191
	v_mul_f32_e32 v192, v196, v192
	v_mul_f32_e32 v193, v197, v193
	v_fma_f32 v190, v194, v190, v194
	v_fma_f32 v191, v195, v191, v195
	v_fma_f32 v192, v196, v192, v196
	v_fma_f32 v193, v197, v193, v197
	v_mul_f32_e32 v190, 0x3f4c422a, v190
	v_mul_f32_e32 v191, 0x3f4c422a, v191
	v_mul_f32_e32 v192, 0x3f4c422a, v192
	v_mul_f32_e32 v193, 0x3f4c422a, v193
	v_mul_f32_e32 v190, 0xc038aa3b, v190
	v_mul_f32_e32 v191, 0xc038aa3b, v191
	v_mul_f32_e32 v192, 0xc038aa3b, v192
	v_mul_f32_e32 v193, 0xc038aa3b, v193
	v_exp_f32_e32 v190, v190
	v_exp_f32_e32 v191, v191
	v_exp_f32_e32 v192, v192
	v_exp_f32_e32 v193, v193
	v_add_f32_e32 v190, 1.0, v190
	v_add_f32_e32 v191, 1.0, v191
	v_add_f32_e32 v192, 1.0, v192
	v_add_f32_e32 v193, 1.0, v193
	v_rcp_f32_e32 v190, v190
	v_rcp_f32_e32 v191, v191
	v_rcp_f32_e32 v192, v192
	v_rcp_f32_e32 v193, v193
	v_pk_mul_f32 v[194:195], v[194:195], v[190:191]
	v_pk_mul_f32 v[196:197], v[196:197], v[192:193]
	v_cvt_pk_bf16_f32 v194, v194, v195
	v_cvt_pk_bf16_f32 v195, v196, v197
	global_store_dwordx2 v[102:103], v[194:195], off
	s_waitcnt vmcnt(15)
; #define GAS __attribute__((address_space(1)))
; __device__ __forceinline__ unsigned pk2(float lo, float hi) { const f32x2cv v = {lo, hi}; return __builtin_bit_cast(unsigned, __builtin_convertvector(v, bf16x2cv)); }
; __device__ __forceinline__ float gelu_tanh(float x) { const float u = 0.7978845608028654f * (x + 0.044715f * x * x * x); return x * __builtin_amdgcn_rcpf(1.0f + __builtin_amdgcn_exp2f(-2.8853900817779268f * u)); }
; __device__ __forceinline__ void ph_s5_out(Frame& F) {
;     ...
;                 for (int k = 0; k < 4; ++k) { const int tloc = 2 * (wave + 8 * i) + (k >> 1), p0 = 8 * (k & 1) + 4 * hh; const size_t m = (size_t)chunk * 64 + tloc;
;                     const v2u uw = *(const GAS v2u*)((chunk < 256 ? (const bf16*)(ws + WS_UG) : (const bf16*)(ws + WS_UGC)) + ug_index(g, (int)m, p0));
;                     const float y0 = gelu_tanh(acc[i][4 * k] + dsk[p0] * bflo(uw.x)), y1 = gelu_tanh(acc[i][4 * k + 1] + dsk[p0 + 1] * bfhi(uw.x));
;                     const float y2 = gelu_tanh(acc[i][4 * k + 2] + dsk[p0 + 2] * bflo(uw.y)), y3 = gelu_tanh(acc[i][4 * k + 3] + dsk[p0 + 3] * bfhi(uw.y));
;                     v2u zw; zw.x = pk2(y0, y1); zw.y = pk2(y2, y3);
;                     *(GAS v2u*)((bf16*)(ws + WS_Z) + m * 512 + 16 * g + p0) = zw; }
	v_lshlrev_b32_e32 v182, 16, v168
	v_and_b32_e32 v183, 0xffff0000, v168
	v_lshlrev_b32_e32 v184, 16, v169
	v_and_b32_e32 v185, 0xffff0000, v169
	v_pk_fma_f32 v[194:195], v[178:179], v[182:183], v[6:7]
	v_pk_fma_f32 v[196:197], v[180:181], v[184:185], v[8:9]
	v_mul_f32_e32 v190, 0x3d372713, v194
	v_mul_f32_e32 v191, 0x3d372713, v195
	v_mul_f32_e32 v192, 0x3d372713, v196
	v_mul_f32_e32 v193, 0x3d372713, v197
	v_mul_f32_e32 v190, v194, v190
	v_mul_f32_e32 v191, v195, v191
	v_mul_f32_e32 v192, v196, v192
	v_mul_f32_e32 v193, v197, v193
	v_fma_f32 v190, v194, v190, v194
	v_fma_f32 v191, v195, v191, v195
	v_fma_f32 v192, v196, v192, v196
	v_fma_f32 v193, v197, v193, v197
	v_mul_f32_e32 v190, 0x3f4c422a, v190
	v_mul_f32_e32 v191, 0x3f4c422a, v191
	v_mul_f32_e32 v192, 0x3f4c422a, v192
	v_mul_f32_e32 v193, 0x3f4c422a, v193
	v_mul_f32_e32 v190, 0xc038aa3b, v190
	v_mul_f32_e32 v191, 0xc038aa3b, v191
	v_mul_f32_e32 v192, 0xc038aa3b, v192
	v_mul_f32_e32 v193, 0xc038aa3b, v193
	v_exp_f32_e32 v190, v190
	v_exp_f32_e32 v191, v191
	v_exp_f32_e32 v192, v192
	v_exp_f32_e32 v193, v193
	v_add_f32_e32 v190, 1.0, v190
	v_add_f32_e32 v191, 1.0, v191
	v_add_f32_e32 v192, 1.0, v192
	v_add_f32_e32 v193, 1.0, v193
	v_rcp_f32_e32 v190, v190
	v_rcp_f32_e32 v191, v191
	v_rcp_f32_e32 v192, v192
	v_rcp_f32_e32 v193, v193
	v_pk_mul_f32 v[194:195], v[194:195], v[190:191]
	v_pk_mul_f32 v[196:197], v[196:197], v[192:193]
	v_cvt_pk_bf16_f32 v194, v194, v195
	v_cvt_pk_bf16_f32 v195, v196, v197
	global_store_dwordx2 v[102:103], v[194:195], off offset:16
	s_waitcnt vmcnt(15)
	v_lshlrev_b32_e32 v182, 16, v170
	v_and_b32_e32 v183, 0xffff0000, v170
	v_lshlrev_b32_e32 v184, 16, v171
	v_and_b32_e32 v185, 0xffff0000, v171
	v_pk_fma_f32 v[194:195], v[174:175], v[182:183], v[10:11]
	v_pk_fma_f32 v[196:197], v[176:177], v[184:185], v[12:13]
	v_mul_f32_e32 v190, 0x3d372713, v194
	v_mul_f32_e32 v191, 0x3d372713, v195
	v_mul_f32_e32 v192, 0x3d372713, v196
	v_mul_f32_e32 v193, 0x3d372713, v197
	v_mul_f32_e32 v190, v194, v190
	v_mul_f32_e32 v191, v195, v191
	v_mul_f32_e32 v192, v196, v192
	v_mul_f32_e32 v193, v197, v193
	v_fma_f32 v190, v194, v190, v194
	v_fma_f32 v191, v195, v191, v195
	v_fma_f32 v192, v196, v192, v196
	v_fma_f32 v193, v197, v193, v197
	v_mul_f32_e32 v190, 0x3f4c422a, v190
	v_mul_f32_e32 v191, 0x3f4c422a, v191
	v_mul_f32_e32 v192, 0x3f4c422a, v192
	v_mul_f32_e32 v193, 0x3f4c422a, v193
	v_mul_f32_e32 v190, 0xc038aa3b, v190
	v_mul_f32_e32 v191, 0xc038aa3b, v191
	v_mul_f32_e32 v192, 0xc038aa3b, v192
	v_mul_f32_e32 v193, 0xc038aa3b, v193
	v_exp_f32_e32 v190, v190
	v_exp_f32_e32 v191, v191
	v_exp_f32_e32 v192, v192
	v_exp_f32_e32 v193, v193
	v_add_f32_e32 v190, 1.0, v190
	v_add_f32_e32 v191, 1.0, v191
	v_add_f32_e32 v192, 1.0, v192
	v_add_f32_e32 v193, 1.0, v193
	v_rcp_f32_e32 v190, v190
	v_rcp_f32_e32 v191, v191
	v_rcp_f32_e32 v192, v192
	v_rcp_f32_e32 v193, v193
	v_pk_mul_f32 v[194:195], v[194:195], v[190:191]
	v_pk_mul_f32 v[196:197], v[196:197], v[192:193]
	v_cvt_pk_bf16_f32 v194, v194, v195
	v_cvt_pk_bf16_f32 v195, v196, v197
	global_store_dwordx2 v[102:103], v[194:195], off offset:1024
	s_waitcnt vmcnt(15)
	v_lshlrev_b32_e32 v182, 16, v172
	v_and_b32_e32 v183, 0xffff0000, v172
	v_lshlrev_b32_e32 v184, 16, v173
	v_and_b32_e32 v185, 0xffff0000, v173
	v_pk_fma_f32 v[194:195], v[178:179], v[182:183], v[14:15]
	v_pk_fma_f32 v[196:197], v[180:181], v[184:185], v[16:17]
	v_mul_f32_e32 v190, 0x3d372713, v194
	v_mul_f32_e32 v191, 0x3d372713, v195
	v_mul_f32_e32 v192, 0x3d372713, v196
	v_mul_f32_e32 v193, 0x3d372713, v197
	v_mul_f32_e32 v190, v194, v190
	v_mul_f32_e32 v191, v195, v191
	v_mul_f32_e32 v192, v196, v192
	v_mul_f32_e32 v193, v197, v193
	v_fma_f32 v190, v194, v190, v194
	v_fma_f32 v191, v195, v191, v195
	v_fma_f32 v192, v196, v192, v196
	v_fma_f32 v193, v197, v193, v197
	v_mul_f32_e32 v190, 0x3f4c422a, v190
	v_mul_f32_e32 v191, 0x3f4c422a, v191
	v_mul_f32_e32 v192, 0x3f4c422a, v192
	v_mul_f32_e32 v193, 0x3f4c422a, v193
	v_mul_f32_e32 v190, 0xc038aa3b, v190
	v_mul_f32_e32 v191, 0xc038aa3b, v191
	v_mul_f32_e32 v192, 0xc038aa3b, v192
	v_mul_f32_e32 v193, 0xc038aa3b, v193
	v_exp_f32_e32 v190, v190
	v_exp_f32_e32 v191, v191
	v_exp_f32_e32 v192, v192
	v_exp_f32_e32 v193, v193
	v_add_f32_e32 v190, 1.0, v190
	v_add_f32_e32 v191, 1.0, v191
	v_add_f32_e32 v192, 1.0, v192
	v_add_f32_e32 v193, 1.0, v193
	v_rcp_f32_e32 v190, v190
	v_rcp_f32_e32 v191, v191
	v_rcp_f32_e32 v192, v192
	v_rcp_f32_e32 v193, v193
	v_pk_mul_f32 v[194:195], v[194:195], v[190:191]
	v_pk_mul_f32 v[196:197], v[196:197], v[192:193]
	v_cvt_pk_bf16_f32 v194, v194, v195
	v_cvt_pk_bf16_f32 v195, v196, v197
	global_store_dwordx2 v[102:103], v[194:195], off offset:1040
	s_branch .LBB0_963
